# in-proj epilogue rewritten by hand: per-block kind dispatch, permlane transposition, dwordx4 stores
# speedup vs baseline: 1.0488x; 1.0488x over previous
; #define OPQ int tid = tid0; asm volatile("" : "+v"(tid));
; template <int K>
; DEV void gemm8_prefetch(const u16* __restrict__ A, const u16* __restrict__ Bt, char* smem, const int tid) {
;   constexpr int HT = 128 * 64;
;   u16* shm = (u16*)smem;
;   const u16* bases[4] = {Bt, A, Bt + (long)128 * K, A + (long)128 * K};
;   const int slots[4] = {4, 0, 5, 1};
; #pragma unroll
;   for (int q = 0; q < 4; ++q)
; #pragma unroll
;     for (int i = 0; i < 2; ++i) {
;       int b = tid * 16 + i * 8192, r, c;
;       g8_stage_rc(b, r, c);
;       __builtin_amdgcn_global_load_lds((const unsigned*)(bases[q] + (long)r * K + c), (unsigned*)((char*)(shm + slots[q] * HT) + b), 16, 0, 0);
;     }
; __global__ void __launch_bounds__(512) mega(Params p, int coop) {
;     ...
;           const int ntile = last ? 8 * 34 + 8 : 9 * 34;
;           auto tile_of = [&](int j, int& tl, int& tf) {
;             if (!last) { tl = j % 9; tf = j / 9; }
;             else if (j < 8 * 34) { tl = 1 + (j & 7); tf = j >> 3; }
;             else { tl = 0; const int q = j - 8 * 34; tf = q == 0 ? 1 : 4 + q; }
;           };
;           __syncthreads();
;           if (xr < ntile) {
;             OPQ
;             int tl, tf;
;             tile_of(xr, tl, tf);
;             gemm8_prefetch<1024>(p.WinT + ((long)l * NINP + tf * 256) * 1024, p.u + (long)(xx * 9 + tl) * 256 * 1024, smem, tid);
.LBB0_163:
	s_or_b64 exec, exec, s[6:7]
	s_cmp_lg_u32 s14, 3
	s_cselect_b64 s[6:7], -1, 0
	v_writelane_b32 v255, s6, 40
	s_cmp_eq_u32 s14, 3
	s_waitcnt lgkmcnt(0)
	v_writelane_b32 v255, s7, 41
	s_cselect_b64 s[6:7], -1, 0
	v_writelane_b32 v255, s6, 42
	s_barrier
	s_nop 0
	v_writelane_b32 v255, s7, 43
	s_and_b64 s[6:7], s[6:7], exec
	s_movk_i32 s6, 0x118
	s_cselect_b32 s15, s6, 0x132
	v_readlane_b32 s6, v254, 59
	s_cmp_lt_i32 s6, s15
	s_barrier
	s_cbranch_scc0 .LBB0_679
	s_lshl_b64 s[6:7], s[24:25], 2
	s_add_u32 s40, s80, s6
	v_mov_b32_e32 v0, v197
	s_addc_u32 s41, s81, s7
	v_readlane_b32 s6, v255, 42
	v_ashrrev_i32_e32 v1, 31, v0
	v_readlane_b32 s7, v255, 43
	v_lshrrev_b32_e32 v1, 26, v1
	s_and_b64 s[6:7], s[6:7], exec
	v_lshlrev_b32_e32 v10, 4, v0
	v_add_u32_e32 v1, v0, v1
	v_bfe_i32 v0, v0, 27, 1
	v_readlane_b32 s6, v254, 12
	v_readlane_b32 s7, v254, 33
	v_lshrrev_b32_e32 v0, 22, v0
	s_cselect_b32 s10, s7, s6
	v_readlane_b32 s6, v254, 11
	v_readlane_b32 s7, v254, 32
	v_add_u32_e32 v0, v10, v0
	s_cselect_b32 s6, s7, s6
	v_and_b32_e32 v0, 0xfffffc00, v0
	s_lshl_b32 s6, s6, 8
	v_sub_u32_e32 v0, v10, v0
	s_mul_i32 s18, s14, 0x2200
	s_ashr_i32 s7, s6, 31
	v_lshrrev_b32_e32 v2, 4, v0
	s_add_u32 s6, s6, s18
	v_bitop3_b32 v2, v2, v0, 32 bitop3:0x6c
	s_addc_u32 s7, s7, 0
	v_readlane_b32 s44, v253, 7
	v_ashrrev_i32_e32 v3, 31, v2
	s_lshl_b64 s[6:7], s[6:7], 11
	v_readlane_b32 s48, v253, 11
	v_lshrrev_b32_e32 v3, 26, v3
	v_readlane_b32 s49, v253, 12
	s_add_u32 s8, s48, s6
	v_readlane_b32 s6, v254, 18
	v_ashrrev_i32_e32 v1, 6, v1
	v_add_u32_e32 v3, v2, v3
	s_addc_u32 s9, s49, s7
	s_add_i32 s6, s10, s6
	v_lshlrev_b32_e32 v0, 3, v1
	v_ashrrev_i32_e32 v4, 6, v3
	v_and_b32_e32 v3, 0xc0, v3
	s_ashr_i32 s7, s6, 31
	v_and_b32_e32 v0, -16, v0
	v_lshlrev_b32_e32 v1, 5, v1
	v_sub_u32_e32 v2, v2, v3
	v_mov_b32_e32 v9, 1
	s_lshl_b64 s[6:7], s[6:7], 19
	v_add_u32_e32 v0, v4, v0
	v_and_b32_e32 v1, 32, v1
	v_ashrrev_i16_sdwa v2, v9, sext(v2) dst_sel:DWORD dst_unused:UNUSED_PAD src0_sel:DWORD src1_sel:BYTE_0
	s_add_u32 s12, s86, s6
	v_add_u32_sdwa v2, v1, sext(v2) dst_sel:DWORD dst_unused:UNUSED_PAD src0_sel:DWORD src1_sel:WORD_0
	v_ashrrev_i32_e32 v1, 31, v0
	s_addc_u32 s13, s87, s7
	v_lshlrev_b64 v[0:1], 11, v[0:1]
	v_ashrrev_i32_e32 v3, 31, v2
	v_add_u32_e32 v6, 0x10000, v10
	v_lshl_add_u64 v[4:5], s[12:13], 0, v[0:1]
	v_lshlrev_b64 v[2:3], 1, v[2:3]
	v_readfirstlane_b32 s16, v6
	v_lshl_add_u64 v[4:5], v[4:5], 0, v[2:3]
	s_mov_b32 m0, s16
	v_add_u32_e32 v11, 0x2000, v10
	global_load_lds_dwordx4 v[4:5], off
	v_ashrrev_i32_e32 v4, 31, v11
	v_lshrrev_b32_e32 v4, 22, v4
	v_add_u32_e32 v4, v11, v4
	v_ashrrev_i32_e32 v5, 10, v4
	v_mul_i32_i24_e32 v4, 0x400, v5
	v_sub_u32_e32 v4, v11, v4
	v_lshrrev_b32_e32 v6, 4, v4
	v_bitop3_b32 v6, v6, v4, 32 bitop3:0x6c
	v_ashrrev_i32_e32 v7, 31, v6
	v_lshrrev_b32_e32 v7, 26, v7
	v_add_u32_e32 v7, v6, v7
	v_lshlrev_b32_e32 v4, 3, v5
	v_ashrrev_i32_e32 v8, 6, v7
	v_and_b32_e32 v7, 0xc0, v7
	v_and_b32_e32 v4, -16, v4
	v_lshlrev_b32_e32 v5, 5, v5
	v_sub_u32_e32 v6, v6, v7
	v_add_u32_e32 v4, v8, v4
	v_and_b32_e32 v5, 32, v5
	v_ashrrev_i16_sdwa v6, v9, sext(v6) dst_sel:DWORD dst_unused:UNUSED_PAD src0_sel:DWORD src1_sel:BYTE_0
	v_add_u32_sdwa v6, v5, sext(v6) dst_sel:DWORD dst_unused:UNUSED_PAD src0_sel:DWORD src1_sel:WORD_0
	v_ashrrev_i32_e32 v5, 31, v4
	v_lshlrev_b64 v[4:5], 11, v[4:5]
	v_ashrrev_i32_e32 v7, 31, v6
	v_add_u32_e32 v12, 0x12000, v10
	s_add_u32 s10, s12, 0x40000
	v_lshl_add_u64 v[8:9], s[12:13], 0, v[4:5]
	v_lshlrev_b64 v[6:7], 1, v[6:7]
	v_readfirstlane_b32 s12, v12
	v_lshl_add_u64 v[8:9], v[8:9], 0, v[6:7]
	s_mov_b32 m0, s12
	v_readfirstlane_b32 s12, v10
	global_load_lds_dwordx4 v[8:9], off
	v_lshl_add_u64 v[8:9], s[8:9], 0, v[0:1]
	s_addc_u32 s11, s13, 0
	v_lshl_add_u64 v[8:9], v[8:9], 0, v[2:3]
	s_mov_b32 m0, s12
	s_add_u32 s6, s8, 0x40000
	global_load_lds_dwordx4 v[8:9], off
	v_lshl_add_u64 v[8:9], s[8:9], 0, v[4:5]
	v_readfirstlane_b32 s8, v11
	v_lshl_add_u64 v[8:9], v[8:9], 0, v[6:7]
	s_mov_b32 m0, s8
	v_add_u32_e32 v11, 0x14000, v10
	s_addc_u32 s7, s9, 0
	global_load_lds_dwordx4 v[8:9], off
	v_lshl_add_u64 v[8:9], s[10:11], 0, v[0:1]
	v_readfirstlane_b32 s8, v11
	v_lshl_add_u64 v[8:9], v[8:9], 0, v[2:3]
	s_mov_b32 m0, s8
	v_add_u32_e32 v11, 0x16000, v10
	v_lshl_add_u64 v[0:1], s[6:7], 0, v[0:1]
	global_load_lds_dwordx4 v[8:9], off
	v_lshl_add_u64 v[8:9], s[10:11], 0, v[4:5]
	v_readfirstlane_b32 s8, v11
	v_lshl_add_u64 v[0:1], v[0:1], 0, v[2:3]
	v_add_u32_e32 v2, 0x4000, v10
	v_lshl_add_u64 v[8:9], v[8:9], 0, v[6:7]
	s_mov_b32 m0, s8
	v_readfirstlane_b32 s8, v2
	global_load_lds_dwordx4 v[8:9], off
	s_mov_b32 m0, s8
	v_add_u32_e32 v2, 0x6000, v10
	global_load_lds_dwordx4 v[0:1], off
	v_lshl_add_u64 v[0:1], s[6:7], 0, v[4:5]
	v_readfirstlane_b32 s6, v2
	v_lshl_add_u64 v[0:1], v[0:1], 0, v[6:7]
	s_mov_b32 m0, s6
	v_readlane_b32 s19, v254, 59
	global_load_lds_dwordx4 v[0:1], off
	v_readlane_b32 s45, v253, 8
	v_readlane_b32 s46, v253, 9
	v_readlane_b32 s47, v253, 10
	v_readlane_b32 s50, v253, 13
	v_readlane_b32 s51, v253, 14
	v_readlane_b32 s52, v253, 15
	v_readlane_b32 s53, v253, 16
	v_readlane_b32 s54, v253, 17
	v_readlane_b32 s55, v253, 18
	v_readlane_b32 s56, v253, 19
	v_readlane_b32 s57, v253, 20
	v_readlane_b32 s58, v253, 21
	v_readlane_b32 s59, v253, 22
	s_branch .LBB0_167
.LBB0_166:
	s_and_b64 vcc, exec, s[42:43]
	s_cbranch_vccnz .LBB0_679

; DEV float sigm(float x) { return rcpf(1.f + ex2(x * -1.4426950408889634f)); }
; DEV float siluf(float x) { return x * sigm(x); }
; DEV void inproj_item(const Params& p, int l, int tt, int tf, int ntt, int ntf, char* smem, int tid) {
;     ...
;   const int wid = tid >> 6, lane = tid & 63, fr = lane & 15, fq = lane >> 4, wr = wid >> 2, wc = wid & 3;
; #pragma unroll
;   for (int ai = 0; ai < 2; ++ai)
; #pragma unroll
;     for (int m = 0; m < 4; ++m) {
;       const int fb = __builtin_amdgcn_readfirstlane(f0 + ai * 128 + wr * 64 + m * 16);
;       const int kind = colkind(fb);
;       if (kind == 5) continue;
;       const int f = fb + fq * 4;
;       float4 lbv = make_float4(0.f, 0.f, 0.f, 0.f);
;       if (kind == 3) lbv = *(const float4*)(p.lb + l * 1024 + (f - C_HF));
;       if (kind == 4) lbv = *(const float4*)(p.lb + l * 1024 + 512 + (f - C_HF - 512));
; #pragma unroll
;       for (int bj = 0; bj < 2; ++bj)
; #pragma unroll
;         for (int n = 0; n < 2; ++n) {
;           const int r = t0 + bj * 128 + wc * 32 + n * 16 + fr;
;           const f32x4 a = acc[ai][bj][m][n];
;           float o0, o1, o2, o3;
;           if (kind == 0) { o0 = a[0]; o1 = a[1]; o2 = a[2]; o3 = a[3]; }
;           else if (kind == 1) { o0 = siluf(a[0]); o1 = siluf(a[1]); o2 = siluf(a[2]); o3 = siluf(a[3]); }
;           else if (kind == 2) { o0 = sigm(a[0]); o1 = sigm(a[1]); o2 = sigm(a[2]); o3 = sigm(a[3]); }
;           else {
;             o0 = (1.f - lbv.x) * sigm(-a[0]); o1 = (1.f - lbv.y) * sigm(-a[1]);
;             o2 = (1.f - lbv.z) * sigm(-a[2]); o3 = (1.f - lbv.w) * sigm(-a[3]);
;           }
;           uint2 o;
;           o.x = pack2(o0, o1);
;           o.y = pack2(o2, o3);
;           *(uint2*)(p.z + (long)r * NINP + f) = o;
;         }
;     }
.LBB0_190:
	v_lshrrev_b32_e32 v184, 1, v148
	v_lshrrev_b32_e32 v186, 8, v148
	v_and_b32_e32 v184, 0x60, v184
	v_readfirstlane_b32 s8, v186
	v_or3_b32 v184, v184, v149, s6
	v_and_b32_e32 v185, 48, v148
	v_mul_u32_u24_e32 v184, s33, v184
	v_lshlrev_b32_e32 v186, 7, v186
	s_lshl_b32 s7, s8, 6
	s_add_i32 s54, s10, s7
	s_lshl_b32 s7, s10, 1
	v_add3_u32 v184, v184, v185, v186
	v_add_u32_e32 v184, s7, v184
	s_mov_b64 s[44:45], s[88:89]
	s_add_u32 s46, s88, 0x44000
	s_addc_u32 s47, s89, 0
	s_add_u32 s48, s88, 0x220000
	s_addc_u32 s49, s89, 0
	s_add_u32 s50, s88, 0x264000
	s_addc_u32 s51, s89, 0
	s_mov_b32 s55, s54
	s_cmpk_lt_u32 s55, 0x1a0
	s_cbranch_scc1 .Lep0_k0
	s_cmpk_lt_u32 s55, 0x3a0
	s_cbranch_scc1 .Lep0_k1
	s_cmpk_lt_u32 s55, 0x7a0
	s_cbranch_scc1 .Lep0_k0
	s_cmpk_lt_u32 s55, 0xba0
	s_cbranch_scc1 .Lep0_k3
	s_cmpk_lt_u32 s55, 0xda0
	s_cbranch_scc1 .Lep0_k1
	s_cmpk_lt_u32 s55, 0x13a0
	s_cbranch_scc1 .Lep0_k0
	s_cmpk_lt_u32 s55, 0x15a0
	s_cbranch_scc1 .Lep0_k1
	s_cmpk_lt_u32 s55, 0x21a0
	s_cbranch_scc0 .Lep0_k0
	v_mul_f32_e32 v160, 0xbfb8aa3b, v124
	v_mul_f32_e32 v161, 0xbfb8aa3b, v125
	v_mul_f32_e32 v162, 0xbfb8aa3b, v126
	v_mul_f32_e32 v163, 0xbfb8aa3b, v127
	v_mul_f32_e32 v164, 0xbfb8aa3b, v120
	v_mul_f32_e32 v165, 0xbfb8aa3b, v121
	v_mul_f32_e32 v166, 0xbfb8aa3b, v122
	v_mul_f32_e32 v167, 0xbfb8aa3b, v123
	v_mul_f32_e32 v168, 0xbfb8aa3b, v116
	v_mul_f32_e32 v169, 0xbfb8aa3b, v117
	v_mul_f32_e32 v170, 0xbfb8aa3b, v118
	v_mul_f32_e32 v171, 0xbfb8aa3b, v119
	v_mul_f32_e32 v172, 0xbfb8aa3b, v112
	v_mul_f32_e32 v173, 0xbfb8aa3b, v113
	v_mul_f32_e32 v174, 0xbfb8aa3b, v114
	v_mul_f32_e32 v175, 0xbfb8aa3b, v115
	v_exp_f32_e32 v160, v160
	v_exp_f32_e32 v161, v161
	v_exp_f32_e32 v162, v162
	v_exp_f32_e32 v163, v163
	v_exp_f32_e32 v164, v164
	v_exp_f32_e32 v165, v165
	v_exp_f32_e32 v166, v166
	v_exp_f32_e32 v167, v167
	v_exp_f32_e32 v168, v168
	v_exp_f32_e32 v169, v169
	v_exp_f32_e32 v170, v170
	v_exp_f32_e32 v171, v171
	v_exp_f32_e32 v172, v172
	v_exp_f32_e32 v173, v173
	v_exp_f32_e32 v174, v174
	v_exp_f32_e32 v175, v175
	v_add_f32_e32 v160, 1.0, v160
	v_add_f32_e32 v161, 1.0, v161
	v_add_f32_e32 v162, 1.0, v162
	v_add_f32_e32 v163, 1.0, v163
	v_add_f32_e32 v164, 1.0, v164
	v_add_f32_e32 v165, 1.0, v165
	v_add_f32_e32 v166, 1.0, v166
	v_add_f32_e32 v167, 1.0, v167
	v_add_f32_e32 v168, 1.0, v168
	v_add_f32_e32 v169, 1.0, v169
	v_add_f32_e32 v170, 1.0, v170
	v_add_f32_e32 v171, 1.0, v171
	v_add_f32_e32 v172, 1.0, v172
	v_add_f32_e32 v173, 1.0, v173
	v_add_f32_e32 v174, 1.0, v174
	v_add_f32_e32 v175, 1.0, v175
	v_rcp_f32_e32 v160, v160
	v_rcp_f32_e32 v161, v161
	v_rcp_f32_e32 v162, v162
	v_rcp_f32_e32 v163, v163
	v_rcp_f32_e32 v164, v164
	v_rcp_f32_e32 v165, v165
	v_rcp_f32_e32 v166, v166
	v_rcp_f32_e32 v167, v167
	v_rcp_f32_e32 v168, v168
	v_rcp_f32_e32 v169, v169
	v_rcp_f32_e32 v170, v170
	v_rcp_f32_e32 v171, v171
	v_rcp_f32_e32 v172, v172
	v_rcp_f32_e32 v173, v173
	v_rcp_f32_e32 v174, v174
	v_rcp_f32_e32 v175, v175
	v_cvt_pk_bf16_f32 v124, v160, v161
	v_cvt_pk_bf16_f32 v125, v162, v163
	v_cvt_pk_bf16_f32 v120, v164, v165
	v_cvt_pk_bf16_f32 v121, v166, v167
	v_cvt_pk_bf16_f32 v116, v168, v169
	v_cvt_pk_bf16_f32 v117, v170, v171
	v_cvt_pk_bf16_f32 v112, v172, v173
	v_cvt_pk_bf16_f32 v113, v174, v175
	s_branch .Lep0_done
.Lep0_k1:
	v_mul_f32_e32 v160, 0xbfb8aa3b, v124
	v_mul_f32_e32 v161, 0xbfb8aa3b, v125
	v_mul_f32_e32 v162, 0xbfb8aa3b, v126
	v_mul_f32_e32 v163, 0xbfb8aa3b, v127
	v_mul_f32_e32 v164, 0xbfb8aa3b, v120
	v_mul_f32_e32 v165, 0xbfb8aa3b, v121
	v_mul_f32_e32 v166, 0xbfb8aa3b, v122
	v_mul_f32_e32 v167, 0xbfb8aa3b, v123
	v_mul_f32_e32 v168, 0xbfb8aa3b, v116
	v_mul_f32_e32 v169, 0xbfb8aa3b, v117
	v_mul_f32_e32 v170, 0xbfb8aa3b, v118
	v_mul_f32_e32 v171, 0xbfb8aa3b, v119
	v_mul_f32_e32 v172, 0xbfb8aa3b, v112
	v_mul_f32_e32 v173, 0xbfb8aa3b, v113
	v_mul_f32_e32 v174, 0xbfb8aa3b, v114
	v_mul_f32_e32 v175, 0xbfb8aa3b, v115
	v_exp_f32_e32 v160, v160
	v_exp_f32_e32 v161, v161
	v_exp_f32_e32 v162, v162
	v_exp_f32_e32 v163, v163
	v_exp_f32_e32 v164, v164
	v_exp_f32_e32 v165, v165
	v_exp_f32_e32 v166, v166
	v_exp_f32_e32 v167, v167
	v_exp_f32_e32 v168, v168
	v_exp_f32_e32 v169, v169
	v_exp_f32_e32 v170, v170
	v_exp_f32_e32 v171, v171
	v_exp_f32_e32 v172, v172
	v_exp_f32_e32 v173, v173
	v_exp_f32_e32 v174, v174
	v_exp_f32_e32 v175, v175
	v_add_f32_e32 v160, 1.0, v160
	v_add_f32_e32 v161, 1.0, v161
	v_add_f32_e32 v162, 1.0, v162
	v_add_f32_e32 v163, 1.0, v163
	v_add_f32_e32 v164, 1.0, v164
	v_add_f32_e32 v165, 1.0, v165
	v_add_f32_e32 v166, 1.0, v166
	v_add_f32_e32 v167, 1.0, v167
	v_add_f32_e32 v168, 1.0, v168
	v_add_f32_e32 v169, 1.0, v169
	v_add_f32_e32 v170, 1.0, v170
	v_add_f32_e32 v171, 1.0, v171
	v_add_f32_e32 v172, 1.0, v172
	v_add_f32_e32 v173, 1.0, v173
	v_add_f32_e32 v174, 1.0, v174
	v_add_f32_e32 v175, 1.0, v175
	v_rcp_f32_e32 v160, v160
	v_rcp_f32_e32 v161, v161
	v_rcp_f32_e32 v162, v162
	v_rcp_f32_e32 v163, v163
	v_rcp_f32_e32 v164, v164
	v_rcp_f32_e32 v165, v165
	v_rcp_f32_e32 v166, v166
	v_rcp_f32_e32 v167, v167
	v_rcp_f32_e32 v168, v168
	v_rcp_f32_e32 v169, v169
	v_rcp_f32_e32 v170, v170
	v_rcp_f32_e32 v171, v171
	v_rcp_f32_e32 v172, v172
	v_rcp_f32_e32 v173, v173
	v_rcp_f32_e32 v174, v174
	v_rcp_f32_e32 v175, v175
	v_pk_mul_f32 v[160:161], v[124:125], v[160:161]
	v_pk_mul_f32 v[162:163], v[126:127], v[162:163]
	v_pk_mul_f32 v[164:165], v[120:121], v[164:165]
	v_pk_mul_f32 v[166:167], v[122:123], v[166:167]
	v_pk_mul_f32 v[168:169], v[116:117], v[168:169]
	v_pk_mul_f32 v[170:171], v[118:119], v[170:171]
	v_pk_mul_f32 v[172:173], v[112:113], v[172:173]
	v_pk_mul_f32 v[174:175], v[114:115], v[174:175]
	v_cvt_pk_bf16_f32 v124, v160, v161
	v_cvt_pk_bf16_f32 v125, v162, v163
	v_cvt_pk_bf16_f32 v120, v164, v165
	v_cvt_pk_bf16_f32 v121, v166, v167
	v_cvt_pk_bf16_f32 v116, v168, v169
	v_cvt_pk_bf16_f32 v117, v170, v171
	v_cvt_pk_bf16_f32 v112, v172, v173
	v_cvt_pk_bf16_f32 v113, v174, v175
	s_branch .Lep0_done
; DEV float sigm(float x) { return rcpf(1.f + ex2(x * -1.4426950408889634f)); }
; DEV float siluf(float x) { return x * sigm(x); }
; DEV void inproj_item(const Params& p, int l, int tt, int tf, int ntt, int ntf, char* smem, int tid) {
;     ...
;   const int wid = tid >> 6, lane = tid & 63, fr = lane & 15, fq = lane >> 4, wr = wid >> 2, wc = wid & 3;
; #pragma unroll
;   for (int ai = 0; ai < 2; ++ai)
; #pragma unroll
;     for (int m = 0; m < 4; ++m) {
;       const int fb = __builtin_amdgcn_readfirstlane(f0 + ai * 128 + wr * 64 + m * 16);
;       const int kind = colkind(fb);
;       if (kind == 5) continue;
;       const int f = fb + fq * 4;
;       float4 lbv = make_float4(0.f, 0.f, 0.f, 0.f);
;       if (kind == 3) lbv = *(const float4*)(p.lb + l * 1024 + (f - C_HF));
;       if (kind == 4) lbv = *(const float4*)(p.lb + l * 1024 + 512 + (f - C_HF - 512));
; #pragma unroll
;       for (int bj = 0; bj < 2; ++bj)
; #pragma unroll
;         for (int n = 0; n < 2; ++n) {
;           const int r = t0 + bj * 128 + wc * 32 + n * 16 + fr;
;           const f32x4 a = acc[ai][bj][m][n];
;           float o0, o1, o2, o3;
;           if (kind == 0) { o0 = a[0]; o1 = a[1]; o2 = a[2]; o3 = a[3]; }
;           else if (kind == 1) { o0 = siluf(a[0]); o1 = siluf(a[1]); o2 = siluf(a[2]); o3 = siluf(a[3]); }
;           else if (kind == 2) { o0 = sigm(a[0]); o1 = sigm(a[1]); o2 = sigm(a[2]); o3 = sigm(a[3]); }
;           else {
;             o0 = (1.f - lbv.x) * sigm(-a[0]); o1 = (1.f - lbv.y) * sigm(-a[1]);
;             o2 = (1.f - lbv.z) * sigm(-a[2]); o3 = (1.f - lbv.w) * sigm(-a[3]);
;           }
;           uint2 o;
;           o.x = pack2(o0, o1);
;           o.y = pack2(o2, o3);
;           *(uint2*)(p.z + (long)r * NINP + f) = o;
;         }
;     }
.Lep0_k3:
	s_add_i32 s7, s55, 0xfffff860
	s_lshl_b32 s7, s7, 2
	s_add_u32 s52, s40, s7
	s_addc_u32 s53, s41, 0
	global_load_dwordx4 v[176:179], v185, s[52:53]
	v_mul_f32_e32 v160, 0x3fb8aa3b, v124
	v_mul_f32_e32 v161, 0x3fb8aa3b, v125
	v_mul_f32_e32 v162, 0x3fb8aa3b, v126
	v_mul_f32_e32 v163, 0x3fb8aa3b, v127
	v_mul_f32_e32 v164, 0x3fb8aa3b, v120
	v_mul_f32_e32 v165, 0x3fb8aa3b, v121
	v_mul_f32_e32 v166, 0x3fb8aa3b, v122
	v_mul_f32_e32 v167, 0x3fb8aa3b, v123
	v_mul_f32_e32 v168, 0x3fb8aa3b, v116
	v_mul_f32_e32 v169, 0x3fb8aa3b, v117
	v_mul_f32_e32 v170, 0x3fb8aa3b, v118
	v_mul_f32_e32 v171, 0x3fb8aa3b, v119
	v_mul_f32_e32 v172, 0x3fb8aa3b, v112
	v_mul_f32_e32 v173, 0x3fb8aa3b, v113
	v_mul_f32_e32 v174, 0x3fb8aa3b, v114
	v_mul_f32_e32 v175, 0x3fb8aa3b, v115
	v_exp_f32_e32 v160, v160
	v_exp_f32_e32 v161, v161
	v_exp_f32_e32 v162, v162
	v_exp_f32_e32 v163, v163
	v_exp_f32_e32 v164, v164
	v_exp_f32_e32 v165, v165
	v_exp_f32_e32 v166, v166
	v_exp_f32_e32 v167, v167
	v_exp_f32_e32 v168, v168
	v_exp_f32_e32 v169, v169
	v_exp_f32_e32 v170, v170
	v_exp_f32_e32 v171, v171
	v_exp_f32_e32 v172, v172
	v_exp_f32_e32 v173, v173
	v_exp_f32_e32 v174, v174
	v_exp_f32_e32 v175, v175
	v_add_f32_e32 v160, 1.0, v160
	v_add_f32_e32 v161, 1.0, v161
	v_add_f32_e32 v162, 1.0, v162
	v_add_f32_e32 v163, 1.0, v163
	v_add_f32_e32 v164, 1.0, v164
	v_add_f32_e32 v165, 1.0, v165
	v_add_f32_e32 v166, 1.0, v166
	v_add_f32_e32 v167, 1.0, v167
	v_add_f32_e32 v168, 1.0, v168
	v_add_f32_e32 v169, 1.0, v169
	v_add_f32_e32 v170, 1.0, v170
	v_add_f32_e32 v171, 1.0, v171
	v_add_f32_e32 v172, 1.0, v172
	v_add_f32_e32 v173, 1.0, v173
	v_add_f32_e32 v174, 1.0, v174
	v_add_f32_e32 v175, 1.0, v175
	v_rcp_f32_e32 v160, v160
	v_rcp_f32_e32 v161, v161
	v_rcp_f32_e32 v162, v162
	v_rcp_f32_e32 v163, v163
	v_rcp_f32_e32 v164, v164
	v_rcp_f32_e32 v165, v165
	v_rcp_f32_e32 v166, v166
	v_rcp_f32_e32 v167, v167
	v_rcp_f32_e32 v168, v168
	v_rcp_f32_e32 v169, v169
	v_rcp_f32_e32 v170, v170
	v_rcp_f32_e32 v171, v171
	v_rcp_f32_e32 v172, v172
	v_rcp_f32_e32 v173, v173
	v_rcp_f32_e32 v174, v174
	v_rcp_f32_e32 v175, v175
	s_waitcnt vmcnt(0)
	v_pk_add_f32 v[180:181], v[176:177], 1.0 op_sel_hi:[1,0] neg_lo:[1,0] neg_hi:[1,0]
	v_pk_add_f32 v[182:183], v[178:179], 1.0 op_sel_hi:[1,0] neg_lo:[1,0] neg_hi:[1,0]
	v_pk_mul_f32 v[160:161], v[160:161], v[180:181]
	v_pk_mul_f32 v[162:163], v[162:163], v[182:183]
	v_pk_mul_f32 v[164:165], v[164:165], v[180:181]
	v_pk_mul_f32 v[166:167], v[166:167], v[182:183]
	v_pk_mul_f32 v[168:169], v[168:169], v[180:181]
	v_pk_mul_f32 v[170:171], v[170:171], v[182:183]
	v_pk_mul_f32 v[172:173], v[172:173], v[180:181]
	v_pk_mul_f32 v[174:175], v[174:175], v[182:183]
	v_cvt_pk_bf16_f32 v124, v160, v161
	v_cvt_pk_bf16_f32 v125, v162, v163
	v_cvt_pk_bf16_f32 v120, v164, v165
	v_cvt_pk_bf16_f32 v121, v166, v167
	v_cvt_pk_bf16_f32 v116, v168, v169
	v_cvt_pk_bf16_f32 v117, v170, v171
	v_cvt_pk_bf16_f32 v112, v172, v173
	v_cvt_pk_bf16_f32 v113, v174, v175
	s_branch .Lep0_done
.Lep0_k0:
	v_cvt_pk_bf16_f32 v124, v124, v125
	v_cvt_pk_bf16_f32 v125, v126, v127
	v_cvt_pk_bf16_f32 v120, v120, v121
	v_cvt_pk_bf16_f32 v121, v122, v123
	v_cvt_pk_bf16_f32 v116, v116, v117
	v_cvt_pk_bf16_f32 v117, v118, v119
	v_cvt_pk_bf16_f32 v112, v112, v113
	v_cvt_pk_bf16_f32 v113, v114, v115
.Lep0_done:
	s_add_i32 s55, s54, 16
	s_cmpk_lt_u32 s55, 0x1a0
	s_cbranch_scc1 .Lep1_k0
	s_cmpk_lt_u32 s55, 0x3a0
	s_cbranch_scc1 .Lep1_k1
	s_cmpk_lt_u32 s55, 0x7a0
	s_cbranch_scc1 .Lep1_k0
	s_cmpk_lt_u32 s55, 0xba0
	s_cbranch_scc1 .Lep1_k3
	s_cmpk_lt_u32 s55, 0xda0
	s_cbranch_scc1 .Lep1_k1
	s_cmpk_lt_u32 s55, 0x13a0
	s_cbranch_scc1 .Lep1_k0
	s_cmpk_lt_u32 s55, 0x15a0
	s_cbranch_scc1 .Lep1_k1
	s_cmpk_lt_u32 s55, 0x21a0
	s_cbranch_scc0 .Lep1_k0
	v_mul_f32_e32 v160, 0xbfb8aa3b, v108
	v_mul_f32_e32 v161, 0xbfb8aa3b, v109
	v_mul_f32_e32 v162, 0xbfb8aa3b, v110
	v_mul_f32_e32 v163, 0xbfb8aa3b, v111
	v_mul_f32_e32 v164, 0xbfb8aa3b, v104
	v_mul_f32_e32 v165, 0xbfb8aa3b, v105
	v_mul_f32_e32 v166, 0xbfb8aa3b, v106
	v_mul_f32_e32 v167, 0xbfb8aa3b, v107
	v_mul_f32_e32 v168, 0xbfb8aa3b, v100
	v_mul_f32_e32 v169, 0xbfb8aa3b, v101
	v_mul_f32_e32 v170, 0xbfb8aa3b, v102
	v_mul_f32_e32 v171, 0xbfb8aa3b, v103
	v_mul_f32_e32 v172, 0xbfb8aa3b, v96
	v_mul_f32_e32 v173, 0xbfb8aa3b, v97
	v_mul_f32_e32 v174, 0xbfb8aa3b, v98
	v_mul_f32_e32 v175, 0xbfb8aa3b, v99
	v_exp_f32_e32 v160, v160
	v_exp_f32_e32 v161, v161
	v_exp_f32_e32 v162, v162
	v_exp_f32_e32 v163, v163
	v_exp_f32_e32 v164, v164
	v_exp_f32_e32 v165, v165
	v_exp_f32_e32 v166, v166
	v_exp_f32_e32 v167, v167
	v_exp_f32_e32 v168, v168
	v_exp_f32_e32 v169, v169
	v_exp_f32_e32 v170, v170
	v_exp_f32_e32 v171, v171
	v_exp_f32_e32 v172, v172
	v_exp_f32_e32 v173, v173
	v_exp_f32_e32 v174, v174
	v_exp_f32_e32 v175, v175
	v_add_f32_e32 v160, 1.0, v160
	v_add_f32_e32 v161, 1.0, v161
	v_add_f32_e32 v162, 1.0, v162
	v_add_f32_e32 v163, 1.0, v163
	v_add_f32_e32 v164, 1.0, v164
	v_add_f32_e32 v165, 1.0, v165
	v_add_f32_e32 v166, 1.0, v166
	v_add_f32_e32 v167, 1.0, v167
	v_add_f32_e32 v168, 1.0, v168
	v_add_f32_e32 v169, 1.0, v169
	v_add_f32_e32 v170, 1.0, v170
	v_add_f32_e32 v171, 1.0, v171
	v_add_f32_e32 v172, 1.0, v172
	v_add_f32_e32 v173, 1.0, v173
	v_add_f32_e32 v174, 1.0, v174
	v_add_f32_e32 v175, 1.0, v175
	v_rcp_f32_e32 v160, v160
	v_rcp_f32_e32 v161, v161
	v_rcp_f32_e32 v162, v162
	v_rcp_f32_e32 v163, v163
	v_rcp_f32_e32 v164, v164
	v_rcp_f32_e32 v165, v165
	v_rcp_f32_e32 v166, v166
	v_rcp_f32_e32 v167, v167
	v_rcp_f32_e32 v168, v168
	v_rcp_f32_e32 v169, v169
	v_rcp_f32_e32 v170, v170
	v_rcp_f32_e32 v171, v171
	v_rcp_f32_e32 v172, v172
	v_rcp_f32_e32 v173, v173
	v_rcp_f32_e32 v174, v174
	v_rcp_f32_e32 v175, v175
	v_cvt_pk_bf16_f32 v126, v160, v161
	v_cvt_pk_bf16_f32 v127, v162, v163
	v_cvt_pk_bf16_f32 v122, v164, v165
	v_cvt_pk_bf16_f32 v123, v166, v167
	v_cvt_pk_bf16_f32 v118, v168, v169
	v_cvt_pk_bf16_f32 v119, v170, v171
	v_cvt_pk_bf16_f32 v114, v172, v173
	v_cvt_pk_bf16_f32 v115, v174, v175
	s_branch .Lep1_done
; DEV float sigm(float x) { return rcpf(1.f + ex2(x * -1.4426950408889634f)); }
; DEV float siluf(float x) { return x * sigm(x); }
; DEV void inproj_item(const Params& p, int l, int tt, int tf, int ntt, int ntf, char* smem, int tid) {
;     ...
;   const int wid = tid >> 6, lane = tid & 63, fr = lane & 15, fq = lane >> 4, wr = wid >> 2, wc = wid & 3;
; #pragma unroll
;   for (int ai = 0; ai < 2; ++ai)
; #pragma unroll
;     for (int m = 0; m < 4; ++m) {
;       const int fb = __builtin_amdgcn_readfirstlane(f0 + ai * 128 + wr * 64 + m * 16);
;       const int kind = colkind(fb);
;       if (kind == 5) continue;
;       const int f = fb + fq * 4;
;       float4 lbv = make_float4(0.f, 0.f, 0.f, 0.f);
;       if (kind == 3) lbv = *(const float4*)(p.lb + l * 1024 + (f - C_HF));
;       if (kind == 4) lbv = *(const float4*)(p.lb + l * 1024 + 512 + (f - C_HF - 512));
; #pragma unroll
;       for (int bj = 0; bj < 2; ++bj)
; #pragma unroll
;         for (int n = 0; n < 2; ++n) {
;           const int r = t0 + bj * 128 + wc * 32 + n * 16 + fr;
;           const f32x4 a = acc[ai][bj][m][n];
;           float o0, o1, o2, o3;
;           if (kind == 0) { o0 = a[0]; o1 = a[1]; o2 = a[2]; o3 = a[3]; }
;           else if (kind == 1) { o0 = siluf(a[0]); o1 = siluf(a[1]); o2 = siluf(a[2]); o3 = siluf(a[3]); }
;           else if (kind == 2) { o0 = sigm(a[0]); o1 = sigm(a[1]); o2 = sigm(a[2]); o3 = sigm(a[3]); }
;           else {
;             o0 = (1.f - lbv.x) * sigm(-a[0]); o1 = (1.f - lbv.y) * sigm(-a[1]);
;             o2 = (1.f - lbv.z) * sigm(-a[2]); o3 = (1.f - lbv.w) * sigm(-a[3]);
;           }
;           uint2 o;
;           o.x = pack2(o0, o1);
;           o.y = pack2(o2, o3);
;           *(uint2*)(p.z + (long)r * NINP + f) = o;
;         }
;     }
.Lep1_k1:
	v_mul_f32_e32 v160, 0xbfb8aa3b, v108
	v_mul_f32_e32 v161, 0xbfb8aa3b, v109
	v_mul_f32_e32 v162, 0xbfb8aa3b, v110
	v_mul_f32_e32 v163, 0xbfb8aa3b, v111
	v_mul_f32_e32 v164, 0xbfb8aa3b, v104
	v_mul_f32_e32 v165, 0xbfb8aa3b, v105
	v_mul_f32_e32 v166, 0xbfb8aa3b, v106
	v_mul_f32_e32 v167, 0xbfb8aa3b, v107
	v_mul_f32_e32 v168, 0xbfb8aa3b, v100
	v_mul_f32_e32 v169, 0xbfb8aa3b, v101
	v_mul_f32_e32 v170, 0xbfb8aa3b, v102
	v_mul_f32_e32 v171, 0xbfb8aa3b, v103
	v_mul_f32_e32 v172, 0xbfb8aa3b, v96
	v_mul_f32_e32 v173, 0xbfb8aa3b, v97
	v_mul_f32_e32 v174, 0xbfb8aa3b, v98
	v_mul_f32_e32 v175, 0xbfb8aa3b, v99
	v_exp_f32_e32 v160, v160
	v_exp_f32_e32 v161, v161
	v_exp_f32_e32 v162, v162
	v_exp_f32_e32 v163, v163
	v_exp_f32_e32 v164, v164
	v_exp_f32_e32 v165, v165
	v_exp_f32_e32 v166, v166
	v_exp_f32_e32 v167, v167
	v_exp_f32_e32 v168, v168
	v_exp_f32_e32 v169, v169
	v_exp_f32_e32 v170, v170
	v_exp_f32_e32 v171, v171
	v_exp_f32_e32 v172, v172
	v_exp_f32_e32 v173, v173
	v_exp_f32_e32 v174, v174
	v_exp_f32_e32 v175, v175
	v_add_f32_e32 v160, 1.0, v160
	v_add_f32_e32 v161, 1.0, v161
	v_add_f32_e32 v162, 1.0, v162
	v_add_f32_e32 v163, 1.0, v163
	v_add_f32_e32 v164, 1.0, v164
	v_add_f32_e32 v165, 1.0, v165
	v_add_f32_e32 v166, 1.0, v166
	v_add_f32_e32 v167, 1.0, v167
	v_add_f32_e32 v168, 1.0, v168
	v_add_f32_e32 v169, 1.0, v169
	v_add_f32_e32 v170, 1.0, v170
	v_add_f32_e32 v171, 1.0, v171
	v_add_f32_e32 v172, 1.0, v172
	v_add_f32_e32 v173, 1.0, v173
	v_add_f32_e32 v174, 1.0, v174
	v_add_f32_e32 v175, 1.0, v175
	v_rcp_f32_e32 v160, v160
	v_rcp_f32_e32 v161, v161
	v_rcp_f32_e32 v162, v162
	v_rcp_f32_e32 v163, v163
	v_rcp_f32_e32 v164, v164
	v_rcp_f32_e32 v165, v165
	v_rcp_f32_e32 v166, v166
	v_rcp_f32_e32 v167, v167
	v_rcp_f32_e32 v168, v168
	v_rcp_f32_e32 v169, v169
	v_rcp_f32_e32 v170, v170
	v_rcp_f32_e32 v171, v171
	v_rcp_f32_e32 v172, v172
	v_rcp_f32_e32 v173, v173
	v_rcp_f32_e32 v174, v174
	v_rcp_f32_e32 v175, v175
	v_pk_mul_f32 v[160:161], v[108:109], v[160:161]
	v_pk_mul_f32 v[162:163], v[110:111], v[162:163]
	v_pk_mul_f32 v[164:165], v[104:105], v[164:165]
	v_pk_mul_f32 v[166:167], v[106:107], v[166:167]
	v_pk_mul_f32 v[168:169], v[100:101], v[168:169]
	v_pk_mul_f32 v[170:171], v[102:103], v[170:171]
	v_pk_mul_f32 v[172:173], v[96:97], v[172:173]
	v_pk_mul_f32 v[174:175], v[98:99], v[174:175]
	v_cvt_pk_bf16_f32 v126, v160, v161
	v_cvt_pk_bf16_f32 v127, v162, v163
	v_cvt_pk_bf16_f32 v122, v164, v165
	v_cvt_pk_bf16_f32 v123, v166, v167
	v_cvt_pk_bf16_f32 v118, v168, v169
	v_cvt_pk_bf16_f32 v119, v170, v171
	v_cvt_pk_bf16_f32 v114, v172, v173
	v_cvt_pk_bf16_f32 v115, v174, v175
	s_branch .Lep1_done
.Lep1_k3:
	s_add_i32 s7, s55, 0xfffff860
	s_lshl_b32 s7, s7, 2
	s_add_u32 s52, s40, s7
	s_addc_u32 s53, s41, 0
	global_load_dwordx4 v[176:179], v185, s[52:53]
	v_mul_f32_e32 v160, 0x3fb8aa3b, v108
	v_mul_f32_e32 v161, 0x3fb8aa3b, v109
	v_mul_f32_e32 v162, 0x3fb8aa3b, v110
	v_mul_f32_e32 v163, 0x3fb8aa3b, v111
	v_mul_f32_e32 v164, 0x3fb8aa3b, v104
	v_mul_f32_e32 v165, 0x3fb8aa3b, v105
	v_mul_f32_e32 v166, 0x3fb8aa3b, v106
	v_mul_f32_e32 v167, 0x3fb8aa3b, v107
	v_mul_f32_e32 v168, 0x3fb8aa3b, v100
	v_mul_f32_e32 v169, 0x3fb8aa3b, v101
	v_mul_f32_e32 v170, 0x3fb8aa3b, v102
	v_mul_f32_e32 v171, 0x3fb8aa3b, v103
	v_mul_f32_e32 v172, 0x3fb8aa3b, v96
	v_mul_f32_e32 v173, 0x3fb8aa3b, v97
	v_mul_f32_e32 v174, 0x3fb8aa3b, v98
	v_mul_f32_e32 v175, 0x3fb8aa3b, v99
	v_exp_f32_e32 v160, v160
	v_exp_f32_e32 v161, v161
	v_exp_f32_e32 v162, v162
	v_exp_f32_e32 v163, v163
	v_exp_f32_e32 v164, v164
	v_exp_f32_e32 v165, v165
	v_exp_f32_e32 v166, v166
	v_exp_f32_e32 v167, v167
	v_exp_f32_e32 v168, v168
	v_exp_f32_e32 v169, v169
	v_exp_f32_e32 v170, v170
	v_exp_f32_e32 v171, v171
	v_exp_f32_e32 v172, v172
	v_exp_f32_e32 v173, v173
	v_exp_f32_e32 v174, v174
	v_exp_f32_e32 v175, v175
	v_add_f32_e32 v160, 1.0, v160
	v_add_f32_e32 v161, 1.0, v161
	v_add_f32_e32 v162, 1.0, v162
	v_add_f32_e32 v163, 1.0, v163
	v_add_f32_e32 v164, 1.0, v164
	v_add_f32_e32 v165, 1.0, v165
	v_add_f32_e32 v166, 1.0, v166
	v_add_f32_e32 v167, 1.0, v167
	v_add_f32_e32 v168, 1.0, v168
	v_add_f32_e32 v169, 1.0, v169
	v_add_f32_e32 v170, 1.0, v170
	v_add_f32_e32 v171, 1.0, v171
	v_add_f32_e32 v172, 1.0, v172
	v_add_f32_e32 v173, 1.0, v173
	v_add_f32_e32 v174, 1.0, v174
	v_add_f32_e32 v175, 1.0, v175
	v_rcp_f32_e32 v160, v160
	v_rcp_f32_e32 v161, v161
	v_rcp_f32_e32 v162, v162
	v_rcp_f32_e32 v163, v163
	v_rcp_f32_e32 v164, v164
	v_rcp_f32_e32 v165, v165
	v_rcp_f32_e32 v166, v166
	v_rcp_f32_e32 v167, v167
	v_rcp_f32_e32 v168, v168
	v_rcp_f32_e32 v169, v169
	v_rcp_f32_e32 v170, v170
	v_rcp_f32_e32 v171, v171
	v_rcp_f32_e32 v172, v172
	v_rcp_f32_e32 v173, v173
	v_rcp_f32_e32 v174, v174
	v_rcp_f32_e32 v175, v175
	s_waitcnt vmcnt(0)
	v_pk_add_f32 v[180:181], v[176:177], 1.0 op_sel_hi:[1,0] neg_lo:[1,0] neg_hi:[1,0]
	v_pk_add_f32 v[182:183], v[178:179], 1.0 op_sel_hi:[1,0] neg_lo:[1,0] neg_hi:[1,0]
	v_pk_mul_f32 v[160:161], v[160:161], v[180:181]
	v_pk_mul_f32 v[162:163], v[162:163], v[182:183]
	v_pk_mul_f32 v[164:165], v[164:165], v[180:181]
	v_pk_mul_f32 v[166:167], v[166:167], v[182:183]
	v_pk_mul_f32 v[168:169], v[168:169], v[180:181]
	v_pk_mul_f32 v[170:171], v[170:171], v[182:183]
	v_pk_mul_f32 v[172:173], v[172:173], v[180:181]
	v_pk_mul_f32 v[174:175], v[174:175], v[182:183]
	v_cvt_pk_bf16_f32 v126, v160, v161
	v_cvt_pk_bf16_f32 v127, v162, v163
	v_cvt_pk_bf16_f32 v122, v164, v165
	v_cvt_pk_bf16_f32 v123, v166, v167
	v_cvt_pk_bf16_f32 v118, v168, v169
	v_cvt_pk_bf16_f32 v119, v170, v171
	v_cvt_pk_bf16_f32 v114, v172, v173
	v_cvt_pk_bf16_f32 v115, v174, v175
	s_branch .Lep1_done
; DEV float sigm(float x) { return rcpf(1.f + ex2(x * -1.4426950408889634f)); }
; DEV float siluf(float x) { return x * sigm(x); }
; DEV void inproj_item(const Params& p, int l, int tt, int tf, int ntt, int ntf, char* smem, int tid) {
;     ...
;   const int wid = tid >> 6, lane = tid & 63, fr = lane & 15, fq = lane >> 4, wr = wid >> 2, wc = wid & 3;
; #pragma unroll
;   for (int ai = 0; ai < 2; ++ai)
; #pragma unroll
;     for (int m = 0; m < 4; ++m) {
;       const int fb = __builtin_amdgcn_readfirstlane(f0 + ai * 128 + wr * 64 + m * 16);
;       const int kind = colkind(fb);
;       if (kind == 5) continue;
;       const int f = fb + fq * 4;
;       float4 lbv = make_float4(0.f, 0.f, 0.f, 0.f);
;       if (kind == 3) lbv = *(const float4*)(p.lb + l * 1024 + (f - C_HF));
;       if (kind == 4) lbv = *(const float4*)(p.lb + l * 1024 + 512 + (f - C_HF - 512));
; #pragma unroll
;       for (int bj = 0; bj < 2; ++bj)
; #pragma unroll
;         for (int n = 0; n < 2; ++n) {
;           const int r = t0 + bj * 128 + wc * 32 + n * 16 + fr;
;           const f32x4 a = acc[ai][bj][m][n];
;           float o0, o1, o2, o3;
;           if (kind == 0) { o0 = a[0]; o1 = a[1]; o2 = a[2]; o3 = a[3]; }
;           else if (kind == 1) { o0 = siluf(a[0]); o1 = siluf(a[1]); o2 = siluf(a[2]); o3 = siluf(a[3]); }
;           else if (kind == 2) { o0 = sigm(a[0]); o1 = sigm(a[1]); o2 = sigm(a[2]); o3 = sigm(a[3]); }
;           else {
;             o0 = (1.f - lbv.x) * sigm(-a[0]); o1 = (1.f - lbv.y) * sigm(-a[1]);
;             o2 = (1.f - lbv.z) * sigm(-a[2]); o3 = (1.f - lbv.w) * sigm(-a[3]);
;           }
;           uint2 o;
;           o.x = pack2(o0, o1);
;           o.y = pack2(o2, o3);
;           *(uint2*)(p.z + (long)r * NINP + f) = o;
;         }
;     }
.Lep1_k0:
	v_cvt_pk_bf16_f32 v126, v108, v109
	v_cvt_pk_bf16_f32 v127, v110, v111
	v_cvt_pk_bf16_f32 v122, v104, v105
	v_cvt_pk_bf16_f32 v123, v106, v107
	v_cvt_pk_bf16_f32 v118, v100, v101
	v_cvt_pk_bf16_f32 v119, v102, v103
	v_cvt_pk_bf16_f32 v114, v96, v97
	v_cvt_pk_bf16_f32 v115, v98, v99
.Lep1_done:
	s_nop 1
	v_permlane32_swap_b32_e32 v124, v126
	v_permlane32_swap_b32_e32 v125, v127
	v_permlane32_swap_b32_e32 v120, v122
	v_permlane32_swap_b32_e32 v121, v123
	v_permlane32_swap_b32_e32 v116, v118
	v_permlane32_swap_b32_e32 v117, v119
	v_permlane32_swap_b32_e32 v112, v114
	v_permlane32_swap_b32_e32 v113, v115
	v_permlane16_swap_b32_e32 v124, v126
	v_permlane16_swap_b32_e32 v125, v127
	v_permlane16_swap_b32_e32 v120, v122
	v_permlane16_swap_b32_e32 v121, v123
	v_permlane16_swap_b32_e32 v116, v118
	v_permlane16_swap_b32_e32 v117, v119
	v_permlane16_swap_b32_e32 v112, v114
	v_permlane16_swap_b32_e32 v113, v115
	global_store_dwordx4 v184, v[124:127], s[44:45]
	global_store_dwordx4 v184, v[120:123], s[46:47]
	global_store_dwordx4 v184, v[116:119], s[48:49]
	global_store_dwordx4 v184, v[112:115], s[50:51]
	s_add_i32 s55, s54, 32
	s_cmpk_lt_u32 s55, 0x1a0
	s_cbranch_scc1 .Lep2_k0
	s_cmpk_lt_u32 s55, 0x3a0
	s_cbranch_scc1 .Lep2_k1
	s_cmpk_lt_u32 s55, 0x7a0
	s_cbranch_scc1 .Lep2_k0
	s_cmpk_lt_u32 s55, 0xba0
	s_cbranch_scc1 .Lep2_k3
	s_cmpk_lt_u32 s55, 0xda0
	s_cbranch_scc1 .Lep2_k1
	s_cmpk_lt_u32 s55, 0x13a0
	s_cbranch_scc1 .Lep2_k0
	s_cmpk_lt_u32 s55, 0x15a0
	s_cbranch_scc1 .Lep2_k1
	s_cmpk_lt_u32 s55, 0x21a0
	s_cbranch_scc0 .Lep2_k0
	v_mul_f32_e32 v160, 0xbfb8aa3b, v92
	v_mul_f32_e32 v161, 0xbfb8aa3b, v93
	v_mul_f32_e32 v162, 0xbfb8aa3b, v94
	v_mul_f32_e32 v163, 0xbfb8aa3b, v95
	v_mul_f32_e32 v164, 0xbfb8aa3b, v88
	v_mul_f32_e32 v165, 0xbfb8aa3b, v89
	v_mul_f32_e32 v166, 0xbfb8aa3b, v90
	v_mul_f32_e32 v167, 0xbfb8aa3b, v91
	v_mul_f32_e32 v168, 0xbfb8aa3b, v84
	v_mul_f32_e32 v169, 0xbfb8aa3b, v85
	v_mul_f32_e32 v170, 0xbfb8aa3b, v86
	v_mul_f32_e32 v171, 0xbfb8aa3b, v87
	v_mul_f32_e32 v172, 0xbfb8aa3b, v80
	v_mul_f32_e32 v173, 0xbfb8aa3b, v81
	v_mul_f32_e32 v174, 0xbfb8aa3b, v82
	v_mul_f32_e32 v175, 0xbfb8aa3b, v83
	v_exp_f32_e32 v160, v160
	v_exp_f32_e32 v161, v161
	v_exp_f32_e32 v162, v162
	v_exp_f32_e32 v163, v163
	v_exp_f32_e32 v164, v164
	v_exp_f32_e32 v165, v165
	v_exp_f32_e32 v166, v166
	v_exp_f32_e32 v167, v167
	v_exp_f32_e32 v168, v168
	v_exp_f32_e32 v169, v169
	v_exp_f32_e32 v170, v170
	v_exp_f32_e32 v171, v171
	v_exp_f32_e32 v172, v172
	v_exp_f32_e32 v173, v173
	v_exp_f32_e32 v174, v174
	v_exp_f32_e32 v175, v175
	v_add_f32_e32 v160, 1.0, v160
	v_add_f32_e32 v161, 1.0, v161
	v_add_f32_e32 v162, 1.0, v162
	v_add_f32_e32 v163, 1.0, v163
	v_add_f32_e32 v164, 1.0, v164
	v_add_f32_e32 v165, 1.0, v165
	v_add_f32_e32 v166, 1.0, v166
	v_add_f32_e32 v167, 1.0, v167
	v_add_f32_e32 v168, 1.0, v168
	v_add_f32_e32 v169, 1.0, v169
	v_add_f32_e32 v170, 1.0, v170
	v_add_f32_e32 v171, 1.0, v171
	v_add_f32_e32 v172, 1.0, v172
	v_add_f32_e32 v173, 1.0, v173
	v_add_f32_e32 v174, 1.0, v174
	v_add_f32_e32 v175, 1.0, v175
	v_rcp_f32_e32 v160, v160
	v_rcp_f32_e32 v161, v161
	v_rcp_f32_e32 v162, v162
	v_rcp_f32_e32 v163, v163
	v_rcp_f32_e32 v164, v164
	v_rcp_f32_e32 v165, v165
	v_rcp_f32_e32 v166, v166
	v_rcp_f32_e32 v167, v167
	v_rcp_f32_e32 v168, v168
	v_rcp_f32_e32 v169, v169
	v_rcp_f32_e32 v170, v170
	v_rcp_f32_e32 v171, v171
	v_rcp_f32_e32 v172, v172
	v_rcp_f32_e32 v173, v173
	v_rcp_f32_e32 v174, v174
	v_rcp_f32_e32 v175, v175
	v_cvt_pk_bf16_f32 v92, v160, v161
	v_cvt_pk_bf16_f32 v93, v162, v163
	v_cvt_pk_bf16_f32 v88, v164, v165
	v_cvt_pk_bf16_f32 v89, v166, v167
	v_cvt_pk_bf16_f32 v84, v168, v169
	v_cvt_pk_bf16_f32 v85, v170, v171
	v_cvt_pk_bf16_f32 v80, v172, v173
	v_cvt_pk_bf16_f32 v81, v174, v175
	s_branch .Lep2_done
.Lep2_k1:
	v_mul_f32_e32 v160, 0xbfb8aa3b, v92
	v_mul_f32_e32 v161, 0xbfb8aa3b, v93
	v_mul_f32_e32 v162, 0xbfb8aa3b, v94
	v_mul_f32_e32 v163, 0xbfb8aa3b, v95
	v_mul_f32_e32 v164, 0xbfb8aa3b, v88
	v_mul_f32_e32 v165, 0xbfb8aa3b, v89
	v_mul_f32_e32 v166, 0xbfb8aa3b, v90
	v_mul_f32_e32 v167, 0xbfb8aa3b, v91
	v_mul_f32_e32 v168, 0xbfb8aa3b, v84
	v_mul_f32_e32 v169, 0xbfb8aa3b, v85
	v_mul_f32_e32 v170, 0xbfb8aa3b, v86
	v_mul_f32_e32 v171, 0xbfb8aa3b, v87
	v_mul_f32_e32 v172, 0xbfb8aa3b, v80
	v_mul_f32_e32 v173, 0xbfb8aa3b, v81
	v_mul_f32_e32 v174, 0xbfb8aa3b, v82
	v_mul_f32_e32 v175, 0xbfb8aa3b, v83
	v_exp_f32_e32 v160, v160
	v_exp_f32_e32 v161, v161
	v_exp_f32_e32 v162, v162
	v_exp_f32_e32 v163, v163
	v_exp_f32_e32 v164, v164
	v_exp_f32_e32 v165, v165
	v_exp_f32_e32 v166, v166
	v_exp_f32_e32 v167, v167
	v_exp_f32_e32 v168, v168
	v_exp_f32_e32 v169, v169
	v_exp_f32_e32 v170, v170
	v_exp_f32_e32 v171, v171
	v_exp_f32_e32 v172, v172
	v_exp_f32_e32 v173, v173
	v_exp_f32_e32 v174, v174
	v_exp_f32_e32 v175, v175
	v_add_f32_e32 v160, 1.0, v160
	v_add_f32_e32 v161, 1.0, v161
	v_add_f32_e32 v162, 1.0, v162
	v_add_f32_e32 v163, 1.0, v163
	v_add_f32_e32 v164, 1.0, v164
	v_add_f32_e32 v165, 1.0, v165
	v_add_f32_e32 v166, 1.0, v166
	v_add_f32_e32 v167, 1.0, v167
	v_add_f32_e32 v168, 1.0, v168
	v_add_f32_e32 v169, 1.0, v169
	v_add_f32_e32 v170, 1.0, v170
	v_add_f32_e32 v171, 1.0, v171
	v_add_f32_e32 v172, 1.0, v172
	v_add_f32_e32 v173, 1.0, v173
	v_add_f32_e32 v174, 1.0, v174
	v_add_f32_e32 v175, 1.0, v175
	v_rcp_f32_e32 v160, v160
	v_rcp_f32_e32 v161, v161
	v_rcp_f32_e32 v162, v162
	v_rcp_f32_e32 v163, v163
	v_rcp_f32_e32 v164, v164
	v_rcp_f32_e32 v165, v165
	v_rcp_f32_e32 v166, v166
	v_rcp_f32_e32 v167, v167
	v_rcp_f32_e32 v168, v168
	v_rcp_f32_e32 v169, v169
	v_rcp_f32_e32 v170, v170
	v_rcp_f32_e32 v171, v171
	v_rcp_f32_e32 v172, v172
	v_rcp_f32_e32 v173, v173
	v_rcp_f32_e32 v174, v174
	v_rcp_f32_e32 v175, v175
	v_pk_mul_f32 v[160:161], v[92:93], v[160:161]
	v_pk_mul_f32 v[162:163], v[94:95], v[162:163]
	v_pk_mul_f32 v[164:165], v[88:89], v[164:165]
	v_pk_mul_f32 v[166:167], v[90:91], v[166:167]
	v_pk_mul_f32 v[168:169], v[84:85], v[168:169]
	v_pk_mul_f32 v[170:171], v[86:87], v[170:171]
	v_pk_mul_f32 v[172:173], v[80:81], v[172:173]
	v_pk_mul_f32 v[174:175], v[82:83], v[174:175]
	v_cvt_pk_bf16_f32 v92, v160, v161
	v_cvt_pk_bf16_f32 v93, v162, v163
	v_cvt_pk_bf16_f32 v88, v164, v165
	v_cvt_pk_bf16_f32 v89, v166, v167
	v_cvt_pk_bf16_f32 v84, v168, v169
	v_cvt_pk_bf16_f32 v85, v170, v171
	v_cvt_pk_bf16_f32 v80, v172, v173
	v_cvt_pk_bf16_f32 v81, v174, v175
	s_branch .Lep2_done
; DEV float sigm(float x) { return rcpf(1.f + ex2(x * -1.4426950408889634f)); }
; DEV float siluf(float x) { return x * sigm(x); }
; DEV void inproj_item(const Params& p, int l, int tt, int tf, int ntt, int ntf, char* smem, int tid) {
;     ...
;   const int wid = tid >> 6, lane = tid & 63, fr = lane & 15, fq = lane >> 4, wr = wid >> 2, wc = wid & 3;
; #pragma unroll
;   for (int ai = 0; ai < 2; ++ai)
; #pragma unroll
;     for (int m = 0; m < 4; ++m) {
;       const int fb = __builtin_amdgcn_readfirstlane(f0 + ai * 128 + wr * 64 + m * 16);
;       const int kind = colkind(fb);
;       if (kind == 5) continue;
;       const int f = fb + fq * 4;
;       float4 lbv = make_float4(0.f, 0.f, 0.f, 0.f);
;       if (kind == 3) lbv = *(const float4*)(p.lb + l * 1024 + (f - C_HF));
;       if (kind == 4) lbv = *(const float4*)(p.lb + l * 1024 + 512 + (f - C_HF - 512));
; #pragma unroll
;       for (int bj = 0; bj < 2; ++bj)
; #pragma unroll
;         for (int n = 0; n < 2; ++n) {
;           const int r = t0 + bj * 128 + wc * 32 + n * 16 + fr;
;           const f32x4 a = acc[ai][bj][m][n];
;           float o0, o1, o2, o3;
;           if (kind == 0) { o0 = a[0]; o1 = a[1]; o2 = a[2]; o3 = a[3]; }
;           else if (kind == 1) { o0 = siluf(a[0]); o1 = siluf(a[1]); o2 = siluf(a[2]); o3 = siluf(a[3]); }
;           else if (kind == 2) { o0 = sigm(a[0]); o1 = sigm(a[1]); o2 = sigm(a[2]); o3 = sigm(a[3]); }
;           else {
;             o0 = (1.f - lbv.x) * sigm(-a[0]); o1 = (1.f - lbv.y) * sigm(-a[1]);
;             o2 = (1.f - lbv.z) * sigm(-a[2]); o3 = (1.f - lbv.w) * sigm(-a[3]);
;           }
;           uint2 o;
;           o.x = pack2(o0, o1);
;           o.y = pack2(o2, o3);
;           *(uint2*)(p.z + (long)r * NINP + f) = o;
;         }
;     }
.Lep2_k3:
	s_add_i32 s7, s55, 0xfffff860
	s_lshl_b32 s7, s7, 2
	s_add_u32 s52, s40, s7
	s_addc_u32 s53, s41, 0
	global_load_dwordx4 v[176:179], v185, s[52:53]
	v_mul_f32_e32 v160, 0x3fb8aa3b, v92
	v_mul_f32_e32 v161, 0x3fb8aa3b, v93
	v_mul_f32_e32 v162, 0x3fb8aa3b, v94
	v_mul_f32_e32 v163, 0x3fb8aa3b, v95
	v_mul_f32_e32 v164, 0x3fb8aa3b, v88
	v_mul_f32_e32 v165, 0x3fb8aa3b, v89
	v_mul_f32_e32 v166, 0x3fb8aa3b, v90
	v_mul_f32_e32 v167, 0x3fb8aa3b, v91
	v_mul_f32_e32 v168, 0x3fb8aa3b, v84
	v_mul_f32_e32 v169, 0x3fb8aa3b, v85
	v_mul_f32_e32 v170, 0x3fb8aa3b, v86
	v_mul_f32_e32 v171, 0x3fb8aa3b, v87
	v_mul_f32_e32 v172, 0x3fb8aa3b, v80
	v_mul_f32_e32 v173, 0x3fb8aa3b, v81
	v_mul_f32_e32 v174, 0x3fb8aa3b, v82
	v_mul_f32_e32 v175, 0x3fb8aa3b, v83
	v_exp_f32_e32 v160, v160
	v_exp_f32_e32 v161, v161
	v_exp_f32_e32 v162, v162
	v_exp_f32_e32 v163, v163
	v_exp_f32_e32 v164, v164
	v_exp_f32_e32 v165, v165
	v_exp_f32_e32 v166, v166
	v_exp_f32_e32 v167, v167
	v_exp_f32_e32 v168, v168
	v_exp_f32_e32 v169, v169
	v_exp_f32_e32 v170, v170
	v_exp_f32_e32 v171, v171
	v_exp_f32_e32 v172, v172
	v_exp_f32_e32 v173, v173
	v_exp_f32_e32 v174, v174
	v_exp_f32_e32 v175, v175
	v_add_f32_e32 v160, 1.0, v160
	v_add_f32_e32 v161, 1.0, v161
	v_add_f32_e32 v162, 1.0, v162
	v_add_f32_e32 v163, 1.0, v163
	v_add_f32_e32 v164, 1.0, v164
	v_add_f32_e32 v165, 1.0, v165
	v_add_f32_e32 v166, 1.0, v166
	v_add_f32_e32 v167, 1.0, v167
	v_add_f32_e32 v168, 1.0, v168
	v_add_f32_e32 v169, 1.0, v169
	v_add_f32_e32 v170, 1.0, v170
	v_add_f32_e32 v171, 1.0, v171
	v_add_f32_e32 v172, 1.0, v172
	v_add_f32_e32 v173, 1.0, v173
	v_add_f32_e32 v174, 1.0, v174
	v_add_f32_e32 v175, 1.0, v175
	v_rcp_f32_e32 v160, v160
	v_rcp_f32_e32 v161, v161
	v_rcp_f32_e32 v162, v162
	v_rcp_f32_e32 v163, v163
	v_rcp_f32_e32 v164, v164
	v_rcp_f32_e32 v165, v165
	v_rcp_f32_e32 v166, v166
	v_rcp_f32_e32 v167, v167
	v_rcp_f32_e32 v168, v168
	v_rcp_f32_e32 v169, v169
	v_rcp_f32_e32 v170, v170
	v_rcp_f32_e32 v171, v171
	v_rcp_f32_e32 v172, v172
	v_rcp_f32_e32 v173, v173
	v_rcp_f32_e32 v174, v174
	v_rcp_f32_e32 v175, v175
	s_waitcnt vmcnt(0)
	v_pk_add_f32 v[180:181], v[176:177], 1.0 op_sel_hi:[1,0] neg_lo:[1,0] neg_hi:[1,0]
	v_pk_add_f32 v[182:183], v[178:179], 1.0 op_sel_hi:[1,0] neg_lo:[1,0] neg_hi:[1,0]
	v_pk_mul_f32 v[160:161], v[160:161], v[180:181]
	v_pk_mul_f32 v[162:163], v[162:163], v[182:183]
	v_pk_mul_f32 v[164:165], v[164:165], v[180:181]
	v_pk_mul_f32 v[166:167], v[166:167], v[182:183]
	v_pk_mul_f32 v[168:169], v[168:169], v[180:181]
	v_pk_mul_f32 v[170:171], v[170:171], v[182:183]
	v_pk_mul_f32 v[172:173], v[172:173], v[180:181]
	v_pk_mul_f32 v[174:175], v[174:175], v[182:183]
	v_cvt_pk_bf16_f32 v92, v160, v161
	v_cvt_pk_bf16_f32 v93, v162, v163
	v_cvt_pk_bf16_f32 v88, v164, v165
	v_cvt_pk_bf16_f32 v89, v166, v167
	v_cvt_pk_bf16_f32 v84, v168, v169
	v_cvt_pk_bf16_f32 v85, v170, v171
	v_cvt_pk_bf16_f32 v80, v172, v173
	v_cvt_pk_bf16_f32 v81, v174, v175
	s_branch .Lep2_done
.Lep2_k0:
	v_cvt_pk_bf16_f32 v92, v92, v93
	v_cvt_pk_bf16_f32 v93, v94, v95
	v_cvt_pk_bf16_f32 v88, v88, v89
	v_cvt_pk_bf16_f32 v89, v90, v91
	v_cvt_pk_bf16_f32 v84, v84, v85
	v_cvt_pk_bf16_f32 v85, v86, v87
	v_cvt_pk_bf16_f32 v80, v80, v81
	v_cvt_pk_bf16_f32 v81, v82, v83
.Lep2_done:
	s_add_i32 s55, s54, 48
	s_cmpk_lt_u32 s55, 0x1a0
	s_cbranch_scc1 .Lep3_k0
	s_cmpk_lt_u32 s55, 0x3a0
	s_cbranch_scc1 .Lep3_k1
	s_cmpk_lt_u32 s55, 0x7a0
	s_cbranch_scc1 .Lep3_k0
	s_cmpk_lt_u32 s55, 0xba0
	s_cbranch_scc1 .Lep3_k3
	s_cmpk_lt_u32 s55, 0xda0
	s_cbranch_scc1 .Lep3_k1
	s_cmpk_lt_u32 s55, 0x13a0
	s_cbranch_scc1 .Lep3_k0
	s_cmpk_lt_u32 s55, 0x15a0
	s_cbranch_scc1 .Lep3_k1
	s_cmpk_lt_u32 s55, 0x21a0
	s_cbranch_scc0 .Lep3_k0
	v_mul_f32_e32 v160, 0xbfb8aa3b, v76
	v_mul_f32_e32 v161, 0xbfb8aa3b, v77
	v_mul_f32_e32 v162, 0xbfb8aa3b, v78
	v_mul_f32_e32 v163, 0xbfb8aa3b, v79
	v_mul_f32_e32 v164, 0xbfb8aa3b, v72
	v_mul_f32_e32 v165, 0xbfb8aa3b, v73
	v_mul_f32_e32 v166, 0xbfb8aa3b, v74
	v_mul_f32_e32 v167, 0xbfb8aa3b, v75
	v_mul_f32_e32 v168, 0xbfb8aa3b, v68
	v_mul_f32_e32 v169, 0xbfb8aa3b, v69
	v_mul_f32_e32 v170, 0xbfb8aa3b, v70
	v_mul_f32_e32 v171, 0xbfb8aa3b, v71
	v_mul_f32_e32 v172, 0xbfb8aa3b, v64
	v_mul_f32_e32 v173, 0xbfb8aa3b, v65
	v_mul_f32_e32 v174, 0xbfb8aa3b, v66
	v_mul_f32_e32 v175, 0xbfb8aa3b, v67
	v_exp_f32_e32 v160, v160
	v_exp_f32_e32 v161, v161
	v_exp_f32_e32 v162, v162
	v_exp_f32_e32 v163, v163
	v_exp_f32_e32 v164, v164
	v_exp_f32_e32 v165, v165
	v_exp_f32_e32 v166, v166
	v_exp_f32_e32 v167, v167
	v_exp_f32_e32 v168, v168
	v_exp_f32_e32 v169, v169
	v_exp_f32_e32 v170, v170
	v_exp_f32_e32 v171, v171
	v_exp_f32_e32 v172, v172
	v_exp_f32_e32 v173, v173
	v_exp_f32_e32 v174, v174
	v_exp_f32_e32 v175, v175
	v_add_f32_e32 v160, 1.0, v160
	v_add_f32_e32 v161, 1.0, v161
	v_add_f32_e32 v162, 1.0, v162
	v_add_f32_e32 v163, 1.0, v163
	v_add_f32_e32 v164, 1.0, v164
	v_add_f32_e32 v165, 1.0, v165
	v_add_f32_e32 v166, 1.0, v166
	v_add_f32_e32 v167, 1.0, v167
	v_add_f32_e32 v168, 1.0, v168
	v_add_f32_e32 v169, 1.0, v169
	v_add_f32_e32 v170, 1.0, v170
	v_add_f32_e32 v171, 1.0, v171
	v_add_f32_e32 v172, 1.0, v172
	v_add_f32_e32 v173, 1.0, v173
	v_add_f32_e32 v174, 1.0, v174
	v_add_f32_e32 v175, 1.0, v175
	v_rcp_f32_e32 v160, v160
	v_rcp_f32_e32 v161, v161
	v_rcp_f32_e32 v162, v162
	v_rcp_f32_e32 v163, v163
	v_rcp_f32_e32 v164, v164
	v_rcp_f32_e32 v165, v165
	v_rcp_f32_e32 v166, v166
	v_rcp_f32_e32 v167, v167
	v_rcp_f32_e32 v168, v168
	v_rcp_f32_e32 v169, v169
	v_rcp_f32_e32 v170, v170
	v_rcp_f32_e32 v171, v171
	v_rcp_f32_e32 v172, v172
	v_rcp_f32_e32 v173, v173
	v_rcp_f32_e32 v174, v174
	v_rcp_f32_e32 v175, v175
	v_cvt_pk_bf16_f32 v94, v160, v161
	v_cvt_pk_bf16_f32 v95, v162, v163
	v_cvt_pk_bf16_f32 v90, v164, v165
	v_cvt_pk_bf16_f32 v91, v166, v167
	v_cvt_pk_bf16_f32 v86, v168, v169
	v_cvt_pk_bf16_f32 v87, v170, v171
	v_cvt_pk_bf16_f32 v82, v172, v173
	v_cvt_pk_bf16_f32 v83, v174, v175
	s_branch .Lep3_done
; DEV float sigm(float x) { return rcpf(1.f + ex2(x * -1.4426950408889634f)); }
; DEV float siluf(float x) { return x * sigm(x); }
; DEV void inproj_item(const Params& p, int l, int tt, int tf, int ntt, int ntf, char* smem, int tid) {
;     ...
;   const int wid = tid >> 6, lane = tid & 63, fr = lane & 15, fq = lane >> 4, wr = wid >> 2, wc = wid & 3;
; #pragma unroll
;   for (int ai = 0; ai < 2; ++ai)
; #pragma unroll
;     for (int m = 0; m < 4; ++m) {
;       const int fb = __builtin_amdgcn_readfirstlane(f0 + ai * 128 + wr * 64 + m * 16);
;       const int kind = colkind(fb);
;       if (kind == 5) continue;
;       const int f = fb + fq * 4;
;       float4 lbv = make_float4(0.f, 0.f, 0.f, 0.f);
;       if (kind == 3) lbv = *(const float4*)(p.lb + l * 1024 + (f - C_HF));
;       if (kind == 4) lbv = *(const float4*)(p.lb + l * 1024 + 512 + (f - C_HF - 512));
; #pragma unroll
;       for (int bj = 0; bj < 2; ++bj)
; #pragma unroll
;         for (int n = 0; n < 2; ++n) {
;           const int r = t0 + bj * 128 + wc * 32 + n * 16 + fr;
;           const f32x4 a = acc[ai][bj][m][n];
;           float o0, o1, o2, o3;
;           if (kind == 0) { o0 = a[0]; o1 = a[1]; o2 = a[2]; o3 = a[3]; }
;           else if (kind == 1) { o0 = siluf(a[0]); o1 = siluf(a[1]); o2 = siluf(a[2]); o3 = siluf(a[3]); }
;           else if (kind == 2) { o0 = sigm(a[0]); o1 = sigm(a[1]); o2 = sigm(a[2]); o3 = sigm(a[3]); }
;           else {
;             o0 = (1.f - lbv.x) * sigm(-a[0]); o1 = (1.f - lbv.y) * sigm(-a[1]);
;             o2 = (1.f - lbv.z) * sigm(-a[2]); o3 = (1.f - lbv.w) * sigm(-a[3]);
;           }
;           uint2 o;
;           o.x = pack2(o0, o1);
;           o.y = pack2(o2, o3);
;           *(uint2*)(p.z + (long)r * NINP + f) = o;
;         }
;     }
.Lep3_k1:
	v_mul_f32_e32 v160, 0xbfb8aa3b, v76
	v_mul_f32_e32 v161, 0xbfb8aa3b, v77
	v_mul_f32_e32 v162, 0xbfb8aa3b, v78
	v_mul_f32_e32 v163, 0xbfb8aa3b, v79
	v_mul_f32_e32 v164, 0xbfb8aa3b, v72
	v_mul_f32_e32 v165, 0xbfb8aa3b, v73
	v_mul_f32_e32 v166, 0xbfb8aa3b, v74
	v_mul_f32_e32 v167, 0xbfb8aa3b, v75
	v_mul_f32_e32 v168, 0xbfb8aa3b, v68
	v_mul_f32_e32 v169, 0xbfb8aa3b, v69
	v_mul_f32_e32 v170, 0xbfb8aa3b, v70
	v_mul_f32_e32 v171, 0xbfb8aa3b, v71
	v_mul_f32_e32 v172, 0xbfb8aa3b, v64
	v_mul_f32_e32 v173, 0xbfb8aa3b, v65
	v_mul_f32_e32 v174, 0xbfb8aa3b, v66
	v_mul_f32_e32 v175, 0xbfb8aa3b, v67
	v_exp_f32_e32 v160, v160
	v_exp_f32_e32 v161, v161
	v_exp_f32_e32 v162, v162
	v_exp_f32_e32 v163, v163
	v_exp_f32_e32 v164, v164
	v_exp_f32_e32 v165, v165
	v_exp_f32_e32 v166, v166
	v_exp_f32_e32 v167, v167
	v_exp_f32_e32 v168, v168
	v_exp_f32_e32 v169, v169
	v_exp_f32_e32 v170, v170
	v_exp_f32_e32 v171, v171
	v_exp_f32_e32 v172, v172
	v_exp_f32_e32 v173, v173
	v_exp_f32_e32 v174, v174
	v_exp_f32_e32 v175, v175
	v_add_f32_e32 v160, 1.0, v160
	v_add_f32_e32 v161, 1.0, v161
	v_add_f32_e32 v162, 1.0, v162
	v_add_f32_e32 v163, 1.0, v163
	v_add_f32_e32 v164, 1.0, v164
	v_add_f32_e32 v165, 1.0, v165
	v_add_f32_e32 v166, 1.0, v166
	v_add_f32_e32 v167, 1.0, v167
	v_add_f32_e32 v168, 1.0, v168
	v_add_f32_e32 v169, 1.0, v169
	v_add_f32_e32 v170, 1.0, v170
	v_add_f32_e32 v171, 1.0, v171
	v_add_f32_e32 v172, 1.0, v172
	v_add_f32_e32 v173, 1.0, v173
	v_add_f32_e32 v174, 1.0, v174
	v_add_f32_e32 v175, 1.0, v175
	v_rcp_f32_e32 v160, v160
	v_rcp_f32_e32 v161, v161
	v_rcp_f32_e32 v162, v162
	v_rcp_f32_e32 v163, v163
	v_rcp_f32_e32 v164, v164
	v_rcp_f32_e32 v165, v165
	v_rcp_f32_e32 v166, v166
	v_rcp_f32_e32 v167, v167
	v_rcp_f32_e32 v168, v168
	v_rcp_f32_e32 v169, v169
	v_rcp_f32_e32 v170, v170
	v_rcp_f32_e32 v171, v171
	v_rcp_f32_e32 v172, v172
	v_rcp_f32_e32 v173, v173
	v_rcp_f32_e32 v174, v174
	v_rcp_f32_e32 v175, v175
	v_pk_mul_f32 v[160:161], v[76:77], v[160:161]
	v_pk_mul_f32 v[162:163], v[78:79], v[162:163]
	v_pk_mul_f32 v[164:165], v[72:73], v[164:165]
	v_pk_mul_f32 v[166:167], v[74:75], v[166:167]
	v_pk_mul_f32 v[168:169], v[68:69], v[168:169]
	v_pk_mul_f32 v[170:171], v[70:71], v[170:171]
	v_pk_mul_f32 v[172:173], v[64:65], v[172:173]
	v_pk_mul_f32 v[174:175], v[66:67], v[174:175]
	v_cvt_pk_bf16_f32 v94, v160, v161
	v_cvt_pk_bf16_f32 v95, v162, v163
	v_cvt_pk_bf16_f32 v90, v164, v165
	v_cvt_pk_bf16_f32 v91, v166, v167
	v_cvt_pk_bf16_f32 v86, v168, v169
	v_cvt_pk_bf16_f32 v87, v170, v171
	v_cvt_pk_bf16_f32 v82, v172, v173
	v_cvt_pk_bf16_f32 v83, v174, v175
	s_branch .Lep3_done
.Lep3_k3:
	s_add_i32 s7, s55, 0xfffff860
	s_lshl_b32 s7, s7, 2
	s_add_u32 s52, s40, s7
	s_addc_u32 s53, s41, 0
	global_load_dwordx4 v[176:179], v185, s[52:53]
	v_mul_f32_e32 v160, 0x3fb8aa3b, v76
	v_mul_f32_e32 v161, 0x3fb8aa3b, v77
	v_mul_f32_e32 v162, 0x3fb8aa3b, v78
	v_mul_f32_e32 v163, 0x3fb8aa3b, v79
	v_mul_f32_e32 v164, 0x3fb8aa3b, v72
	v_mul_f32_e32 v165, 0x3fb8aa3b, v73
	v_mul_f32_e32 v166, 0x3fb8aa3b, v74
	v_mul_f32_e32 v167, 0x3fb8aa3b, v75
	v_mul_f32_e32 v168, 0x3fb8aa3b, v68
	v_mul_f32_e32 v169, 0x3fb8aa3b, v69
	v_mul_f32_e32 v170, 0x3fb8aa3b, v70
	v_mul_f32_e32 v171, 0x3fb8aa3b, v71
	v_mul_f32_e32 v172, 0x3fb8aa3b, v64
	v_mul_f32_e32 v173, 0x3fb8aa3b, v65
	v_mul_f32_e32 v174, 0x3fb8aa3b, v66
	v_mul_f32_e32 v175, 0x3fb8aa3b, v67
	v_exp_f32_e32 v160, v160
	v_exp_f32_e32 v161, v161
	v_exp_f32_e32 v162, v162
	v_exp_f32_e32 v163, v163
	v_exp_f32_e32 v164, v164
	v_exp_f32_e32 v165, v165
	v_exp_f32_e32 v166, v166
	v_exp_f32_e32 v167, v167
	v_exp_f32_e32 v168, v168
	v_exp_f32_e32 v169, v169
	v_exp_f32_e32 v170, v170
	v_exp_f32_e32 v171, v171
	v_exp_f32_e32 v172, v172
	v_exp_f32_e32 v173, v173
	v_exp_f32_e32 v174, v174
	v_exp_f32_e32 v175, v175
	v_add_f32_e32 v160, 1.0, v160
	v_add_f32_e32 v161, 1.0, v161
	v_add_f32_e32 v162, 1.0, v162
	v_add_f32_e32 v163, 1.0, v163
	v_add_f32_e32 v164, 1.0, v164
	v_add_f32_e32 v165, 1.0, v165
	v_add_f32_e32 v166, 1.0, v166
	v_add_f32_e32 v167, 1.0, v167
	v_add_f32_e32 v168, 1.0, v168
	v_add_f32_e32 v169, 1.0, v169
	v_add_f32_e32 v170, 1.0, v170
	v_add_f32_e32 v171, 1.0, v171
	v_add_f32_e32 v172, 1.0, v172
	v_add_f32_e32 v173, 1.0, v173
	v_add_f32_e32 v174, 1.0, v174
	v_add_f32_e32 v175, 1.0, v175
	v_rcp_f32_e32 v160, v160
	v_rcp_f32_e32 v161, v161
	v_rcp_f32_e32 v162, v162
	v_rcp_f32_e32 v163, v163
	v_rcp_f32_e32 v164, v164
	v_rcp_f32_e32 v165, v165
	v_rcp_f32_e32 v166, v166
	v_rcp_f32_e32 v167, v167
	v_rcp_f32_e32 v168, v168
	v_rcp_f32_e32 v169, v169
	v_rcp_f32_e32 v170, v170
	v_rcp_f32_e32 v171, v171
	v_rcp_f32_e32 v172, v172
	v_rcp_f32_e32 v173, v173
	v_rcp_f32_e32 v174, v174
	v_rcp_f32_e32 v175, v175
	s_waitcnt vmcnt(0)
	v_pk_add_f32 v[180:181], v[176:177], 1.0 op_sel_hi:[1,0] neg_lo:[1,0] neg_hi:[1,0]
	v_pk_add_f32 v[182:183], v[178:179], 1.0 op_sel_hi:[1,0] neg_lo:[1,0] neg_hi:[1,0]
	v_pk_mul_f32 v[160:161], v[160:161], v[180:181]
	v_pk_mul_f32 v[162:163], v[162:163], v[182:183]
	v_pk_mul_f32 v[164:165], v[164:165], v[180:181]
	v_pk_mul_f32 v[166:167], v[166:167], v[182:183]
	v_pk_mul_f32 v[168:169], v[168:169], v[180:181]
	v_pk_mul_f32 v[170:171], v[170:171], v[182:183]
	v_pk_mul_f32 v[172:173], v[172:173], v[180:181]
	v_pk_mul_f32 v[174:175], v[174:175], v[182:183]
	v_cvt_pk_bf16_f32 v94, v160, v161
	v_cvt_pk_bf16_f32 v95, v162, v163
	v_cvt_pk_bf16_f32 v90, v164, v165
	v_cvt_pk_bf16_f32 v91, v166, v167
	v_cvt_pk_bf16_f32 v86, v168, v169
	v_cvt_pk_bf16_f32 v87, v170, v171
	v_cvt_pk_bf16_f32 v82, v172, v173
	v_cvt_pk_bf16_f32 v83, v174, v175
	s_branch .Lep3_done
; DEV float sigm(float x) { return rcpf(1.f + ex2(x * -1.4426950408889634f)); }
; DEV float siluf(float x) { return x * sigm(x); }
; DEV void inproj_item(const Params& p, int l, int tt, int tf, int ntt, int ntf, char* smem, int tid) {
;     ...
;   const int wid = tid >> 6, lane = tid & 63, fr = lane & 15, fq = lane >> 4, wr = wid >> 2, wc = wid & 3;
; #pragma unroll
;   for (int ai = 0; ai < 2; ++ai)
; #pragma unroll
;     for (int m = 0; m < 4; ++m) {
;       const int fb = __builtin_amdgcn_readfirstlane(f0 + ai * 128 + wr * 64 + m * 16);
;       const int kind = colkind(fb);
;       if (kind == 5) continue;
;       const int f = fb + fq * 4;
;       float4 lbv = make_float4(0.f, 0.f, 0.f, 0.f);
;       if (kind == 3) lbv = *(const float4*)(p.lb + l * 1024 + (f - C_HF));
;       if (kind == 4) lbv = *(const float4*)(p.lb + l * 1024 + 512 + (f - C_HF - 512));
; #pragma unroll
;       for (int bj = 0; bj < 2; ++bj)
; #pragma unroll
;         for (int n = 0; n < 2; ++n) {
;           const int r = t0 + bj * 128 + wc * 32 + n * 16 + fr;
;           const f32x4 a = acc[ai][bj][m][n];
;           float o0, o1, o2, o3;
;           if (kind == 0) { o0 = a[0]; o1 = a[1]; o2 = a[2]; o3 = a[3]; }
;           else if (kind == 1) { o0 = siluf(a[0]); o1 = siluf(a[1]); o2 = siluf(a[2]); o3 = siluf(a[3]); }
;           else if (kind == 2) { o0 = sigm(a[0]); o1 = sigm(a[1]); o2 = sigm(a[2]); o3 = sigm(a[3]); }
;           else {
;             o0 = (1.f - lbv.x) * sigm(-a[0]); o1 = (1.f - lbv.y) * sigm(-a[1]);
;             o2 = (1.f - lbv.z) * sigm(-a[2]); o3 = (1.f - lbv.w) * sigm(-a[3]);
;           }
;           uint2 o;
;           o.x = pack2(o0, o1);
;           o.y = pack2(o2, o3);
;           *(uint2*)(p.z + (long)r * NINP + f) = o;
;         }
;     }
.Lep3_k0:
	v_cvt_pk_bf16_f32 v94, v76, v77
	v_cvt_pk_bf16_f32 v95, v78, v79
	v_cvt_pk_bf16_f32 v90, v72, v73
	v_cvt_pk_bf16_f32 v91, v74, v75
	v_cvt_pk_bf16_f32 v86, v68, v69
	v_cvt_pk_bf16_f32 v87, v70, v71
	v_cvt_pk_bf16_f32 v82, v64, v65
	v_cvt_pk_bf16_f32 v83, v66, v67
.Lep3_done:
	s_nop 1
	v_permlane32_swap_b32_e32 v92, v94
	v_permlane32_swap_b32_e32 v93, v95
	v_permlane32_swap_b32_e32 v88, v90
	v_permlane32_swap_b32_e32 v89, v91
	v_permlane32_swap_b32_e32 v84, v86
	v_permlane32_swap_b32_e32 v85, v87
	v_permlane32_swap_b32_e32 v80, v82
	v_permlane32_swap_b32_e32 v81, v83
	v_permlane16_swap_b32_e32 v92, v94
	v_permlane16_swap_b32_e32 v93, v95
	v_permlane16_swap_b32_e32 v88, v90
	v_permlane16_swap_b32_e32 v89, v91
	v_permlane16_swap_b32_e32 v84, v86
	v_permlane16_swap_b32_e32 v85, v87
	v_permlane16_swap_b32_e32 v80, v82
	v_permlane16_swap_b32_e32 v81, v83
	global_store_dwordx4 v184, v[92:95], s[44:45] offset:64
	global_store_dwordx4 v184, v[88:91], s[46:47] offset:64
	global_store_dwordx4 v184, v[84:87], s[48:49] offset:64
	global_store_dwordx4 v184, v[80:83], s[50:51] offset:64
	s_add_i32 s55, s54, 128
	s_cmpk_lt_u32 s55, 0x1a0
	s_cbranch_scc1 .Lep4_k0
	s_cmpk_lt_u32 s55, 0x3a0
	s_cbranch_scc1 .Lep4_k1
	s_cmpk_lt_u32 s55, 0x7a0
	s_cbranch_scc1 .Lep4_k0
	s_cmpk_lt_u32 s55, 0xba0
	s_cbranch_scc1 .Lep4_k3
	s_cmpk_lt_u32 s55, 0xda0
	s_cbranch_scc1 .Lep4_k1
	s_cmpk_lt_u32 s55, 0x13a0
	s_cbranch_scc1 .Lep4_k0
	s_cmpk_lt_u32 s55, 0x15a0
	s_cbranch_scc1 .Lep4_k1
	s_cmpk_lt_u32 s55, 0x21a0
	s_cbranch_scc0 .Lep4_k0
	v_mul_f32_e32 v160, 0xbfb8aa3b, v60
	v_mul_f32_e32 v161, 0xbfb8aa3b, v61
	v_mul_f32_e32 v162, 0xbfb8aa3b, v62
	v_mul_f32_e32 v163, 0xbfb8aa3b, v63
	v_mul_f32_e32 v164, 0xbfb8aa3b, v56
	v_mul_f32_e32 v165, 0xbfb8aa3b, v57
	v_mul_f32_e32 v166, 0xbfb8aa3b, v58
	v_mul_f32_e32 v167, 0xbfb8aa3b, v59
	v_mul_f32_e32 v168, 0xbfb8aa3b, v52
	v_mul_f32_e32 v169, 0xbfb8aa3b, v53
	v_mul_f32_e32 v170, 0xbfb8aa3b, v54
	v_mul_f32_e32 v171, 0xbfb8aa3b, v55
	v_mul_f32_e32 v172, 0xbfb8aa3b, v48
	v_mul_f32_e32 v173, 0xbfb8aa3b, v49
	v_mul_f32_e32 v174, 0xbfb8aa3b, v50
	v_mul_f32_e32 v175, 0xbfb8aa3b, v51
	v_exp_f32_e32 v160, v160
	v_exp_f32_e32 v161, v161
	v_exp_f32_e32 v162, v162
	v_exp_f32_e32 v163, v163
	v_exp_f32_e32 v164, v164
	v_exp_f32_e32 v165, v165
	v_exp_f32_e32 v166, v166
	v_exp_f32_e32 v167, v167
	v_exp_f32_e32 v168, v168
	v_exp_f32_e32 v169, v169
	v_exp_f32_e32 v170, v170
	v_exp_f32_e32 v171, v171
	v_exp_f32_e32 v172, v172
	v_exp_f32_e32 v173, v173
	v_exp_f32_e32 v174, v174
	v_exp_f32_e32 v175, v175
	v_add_f32_e32 v160, 1.0, v160
	v_add_f32_e32 v161, 1.0, v161
	v_add_f32_e32 v162, 1.0, v162
	v_add_f32_e32 v163, 1.0, v163
	v_add_f32_e32 v164, 1.0, v164
	v_add_f32_e32 v165, 1.0, v165
	v_add_f32_e32 v166, 1.0, v166
	v_add_f32_e32 v167, 1.0, v167
	v_add_f32_e32 v168, 1.0, v168
	v_add_f32_e32 v169, 1.0, v169
	v_add_f32_e32 v170, 1.0, v170
	v_add_f32_e32 v171, 1.0, v171
	v_add_f32_e32 v172, 1.0, v172
	v_add_f32_e32 v173, 1.0, v173
	v_add_f32_e32 v174, 1.0, v174
	v_add_f32_e32 v175, 1.0, v175
	v_rcp_f32_e32 v160, v160
	v_rcp_f32_e32 v161, v161
	v_rcp_f32_e32 v162, v162
	v_rcp_f32_e32 v163, v163
	v_rcp_f32_e32 v164, v164
	v_rcp_f32_e32 v165, v165
	v_rcp_f32_e32 v166, v166
	v_rcp_f32_e32 v167, v167
	v_rcp_f32_e32 v168, v168
	v_rcp_f32_e32 v169, v169
	v_rcp_f32_e32 v170, v170
	v_rcp_f32_e32 v171, v171
	v_rcp_f32_e32 v172, v172
	v_rcp_f32_e32 v173, v173
	v_rcp_f32_e32 v174, v174
	v_rcp_f32_e32 v175, v175
	v_cvt_pk_bf16_f32 v60, v160, v161
	v_cvt_pk_bf16_f32 v61, v162, v163
	v_cvt_pk_bf16_f32 v56, v164, v165
	v_cvt_pk_bf16_f32 v57, v166, v167
	v_cvt_pk_bf16_f32 v52, v168, v169
	v_cvt_pk_bf16_f32 v53, v170, v171
	v_cvt_pk_bf16_f32 v48, v172, v173
	v_cvt_pk_bf16_f32 v49, v174, v175
	s_branch .Lep4_done
.Lep4_k1:
	v_mul_f32_e32 v160, 0xbfb8aa3b, v60
	v_mul_f32_e32 v161, 0xbfb8aa3b, v61
	v_mul_f32_e32 v162, 0xbfb8aa3b, v62
	v_mul_f32_e32 v163, 0xbfb8aa3b, v63
	v_mul_f32_e32 v164, 0xbfb8aa3b, v56
	v_mul_f32_e32 v165, 0xbfb8aa3b, v57
	v_mul_f32_e32 v166, 0xbfb8aa3b, v58
	v_mul_f32_e32 v167, 0xbfb8aa3b, v59
	v_mul_f32_e32 v168, 0xbfb8aa3b, v52
	v_mul_f32_e32 v169, 0xbfb8aa3b, v53
	v_mul_f32_e32 v170, 0xbfb8aa3b, v54
	v_mul_f32_e32 v171, 0xbfb8aa3b, v55
	v_mul_f32_e32 v172, 0xbfb8aa3b, v48
	v_mul_f32_e32 v173, 0xbfb8aa3b, v49
	v_mul_f32_e32 v174, 0xbfb8aa3b, v50
	v_mul_f32_e32 v175, 0xbfb8aa3b, v51
	v_exp_f32_e32 v160, v160
	v_exp_f32_e32 v161, v161
	v_exp_f32_e32 v162, v162
	v_exp_f32_e32 v163, v163
	v_exp_f32_e32 v164, v164
	v_exp_f32_e32 v165, v165
	v_exp_f32_e32 v166, v166
	v_exp_f32_e32 v167, v167
	v_exp_f32_e32 v168, v168
	v_exp_f32_e32 v169, v169
	v_exp_f32_e32 v170, v170
	v_exp_f32_e32 v171, v171
	v_exp_f32_e32 v172, v172
	v_exp_f32_e32 v173, v173
	v_exp_f32_e32 v174, v174
	v_exp_f32_e32 v175, v175
	v_add_f32_e32 v160, 1.0, v160
	v_add_f32_e32 v161, 1.0, v161
	v_add_f32_e32 v162, 1.0, v162
	v_add_f32_e32 v163, 1.0, v163
	v_add_f32_e32 v164, 1.0, v164
	v_add_f32_e32 v165, 1.0, v165
	v_add_f32_e32 v166, 1.0, v166
	v_add_f32_e32 v167, 1.0, v167
	v_add_f32_e32 v168, 1.0, v168
	v_add_f32_e32 v169, 1.0, v169
	v_add_f32_e32 v170, 1.0, v170
	v_add_f32_e32 v171, 1.0, v171
	v_add_f32_e32 v172, 1.0, v172
	v_add_f32_e32 v173, 1.0, v173
	v_add_f32_e32 v174, 1.0, v174
	v_add_f32_e32 v175, 1.0, v175
	v_rcp_f32_e32 v160, v160
	v_rcp_f32_e32 v161, v161
	v_rcp_f32_e32 v162, v162
	v_rcp_f32_e32 v163, v163
	v_rcp_f32_e32 v164, v164
	v_rcp_f32_e32 v165, v165
	v_rcp_f32_e32 v166, v166
	v_rcp_f32_e32 v167, v167
	v_rcp_f32_e32 v168, v168
	v_rcp_f32_e32 v169, v169
	v_rcp_f32_e32 v170, v170
	v_rcp_f32_e32 v171, v171
	v_rcp_f32_e32 v172, v172
	v_rcp_f32_e32 v173, v173
	v_rcp_f32_e32 v174, v174
	v_rcp_f32_e32 v175, v175
	v_pk_mul_f32 v[160:161], v[60:61], v[160:161]
	v_pk_mul_f32 v[162:163], v[62:63], v[162:163]
	v_pk_mul_f32 v[164:165], v[56:57], v[164:165]
	v_pk_mul_f32 v[166:167], v[58:59], v[166:167]
	v_pk_mul_f32 v[168:169], v[52:53], v[168:169]
	v_pk_mul_f32 v[170:171], v[54:55], v[170:171]
	v_pk_mul_f32 v[172:173], v[48:49], v[172:173]
	v_pk_mul_f32 v[174:175], v[50:51], v[174:175]
	v_cvt_pk_bf16_f32 v60, v160, v161
	v_cvt_pk_bf16_f32 v61, v162, v163
	v_cvt_pk_bf16_f32 v56, v164, v165
	v_cvt_pk_bf16_f32 v57, v166, v167
	v_cvt_pk_bf16_f32 v52, v168, v169
	v_cvt_pk_bf16_f32 v53, v170, v171
	v_cvt_pk_bf16_f32 v48, v172, v173
	v_cvt_pk_bf16_f32 v49, v174, v175
	s_branch .Lep4_done
; DEV float sigm(float x) { return rcpf(1.f + ex2(x * -1.4426950408889634f)); }
; DEV float siluf(float x) { return x * sigm(x); }
; DEV void inproj_item(const Params& p, int l, int tt, int tf, int ntt, int ntf, char* smem, int tid) {
;     ...
;   const int wid = tid >> 6, lane = tid & 63, fr = lane & 15, fq = lane >> 4, wr = wid >> 2, wc = wid & 3;
; #pragma unroll
;   for (int ai = 0; ai < 2; ++ai)
; #pragma unroll
;     for (int m = 0; m < 4; ++m) {
;       const int fb = __builtin_amdgcn_readfirstlane(f0 + ai * 128 + wr * 64 + m * 16);
;       const int kind = colkind(fb);
;       if (kind == 5) continue;
;       const int f = fb + fq * 4;
;       float4 lbv = make_float4(0.f, 0.f, 0.f, 0.f);
;       if (kind == 3) lbv = *(const float4*)(p.lb + l * 1024 + (f - C_HF));
;       if (kind == 4) lbv = *(const float4*)(p.lb + l * 1024 + 512 + (f - C_HF - 512));
; #pragma unroll
;       for (int bj = 0; bj < 2; ++bj)
; #pragma unroll
;         for (int n = 0; n < 2; ++n) {
;           const int r = t0 + bj * 128 + wc * 32 + n * 16 + fr;
;           const f32x4 a = acc[ai][bj][m][n];
;           float o0, o1, o2, o3;
;           if (kind == 0) { o0 = a[0]; o1 = a[1]; o2 = a[2]; o3 = a[3]; }
;           else if (kind == 1) { o0 = siluf(a[0]); o1 = siluf(a[1]); o2 = siluf(a[2]); o3 = siluf(a[3]); }
;           else if (kind == 2) { o0 = sigm(a[0]); o1 = sigm(a[1]); o2 = sigm(a[2]); o3 = sigm(a[3]); }
;           else {
;             o0 = (1.f - lbv.x) * sigm(-a[0]); o1 = (1.f - lbv.y) * sigm(-a[1]);
;             o2 = (1.f - lbv.z) * sigm(-a[2]); o3 = (1.f - lbv.w) * sigm(-a[3]);
;           }
;           uint2 o;
;           o.x = pack2(o0, o1);
;           o.y = pack2(o2, o3);
;           *(uint2*)(p.z + (long)r * NINP + f) = o;
;         }
;     }
.Lep4_k3:
	s_add_i32 s7, s55, 0xfffff860
	s_lshl_b32 s7, s7, 2
	s_add_u32 s52, s40, s7
	s_addc_u32 s53, s41, 0
	global_load_dwordx4 v[176:179], v185, s[52:53]
	v_mul_f32_e32 v160, 0x3fb8aa3b, v60
	v_mul_f32_e32 v161, 0x3fb8aa3b, v61
	v_mul_f32_e32 v162, 0x3fb8aa3b, v62
	v_mul_f32_e32 v163, 0x3fb8aa3b, v63
	v_mul_f32_e32 v164, 0x3fb8aa3b, v56
	v_mul_f32_e32 v165, 0x3fb8aa3b, v57
	v_mul_f32_e32 v166, 0x3fb8aa3b, v58
	v_mul_f32_e32 v167, 0x3fb8aa3b, v59
	v_mul_f32_e32 v168, 0x3fb8aa3b, v52
	v_mul_f32_e32 v169, 0x3fb8aa3b, v53
	v_mul_f32_e32 v170, 0x3fb8aa3b, v54
	v_mul_f32_e32 v171, 0x3fb8aa3b, v55
	v_mul_f32_e32 v172, 0x3fb8aa3b, v48
	v_mul_f32_e32 v173, 0x3fb8aa3b, v49
	v_mul_f32_e32 v174, 0x3fb8aa3b, v50
	v_mul_f32_e32 v175, 0x3fb8aa3b, v51
	v_exp_f32_e32 v160, v160
	v_exp_f32_e32 v161, v161
	v_exp_f32_e32 v162, v162
	v_exp_f32_e32 v163, v163
	v_exp_f32_e32 v164, v164
	v_exp_f32_e32 v165, v165
	v_exp_f32_e32 v166, v166
	v_exp_f32_e32 v167, v167
	v_exp_f32_e32 v168, v168
	v_exp_f32_e32 v169, v169
	v_exp_f32_e32 v170, v170
	v_exp_f32_e32 v171, v171
	v_exp_f32_e32 v172, v172
	v_exp_f32_e32 v173, v173
	v_exp_f32_e32 v174, v174
	v_exp_f32_e32 v175, v175
	v_add_f32_e32 v160, 1.0, v160
	v_add_f32_e32 v161, 1.0, v161
	v_add_f32_e32 v162, 1.0, v162
	v_add_f32_e32 v163, 1.0, v163
	v_add_f32_e32 v164, 1.0, v164
	v_add_f32_e32 v165, 1.0, v165
	v_add_f32_e32 v166, 1.0, v166
	v_add_f32_e32 v167, 1.0, v167
	v_add_f32_e32 v168, 1.0, v168
	v_add_f32_e32 v169, 1.0, v169
	v_add_f32_e32 v170, 1.0, v170
	v_add_f32_e32 v171, 1.0, v171
	v_add_f32_e32 v172, 1.0, v172
	v_add_f32_e32 v173, 1.0, v173
	v_add_f32_e32 v174, 1.0, v174
	v_add_f32_e32 v175, 1.0, v175
	v_rcp_f32_e32 v160, v160
	v_rcp_f32_e32 v161, v161
	v_rcp_f32_e32 v162, v162
	v_rcp_f32_e32 v163, v163
	v_rcp_f32_e32 v164, v164
	v_rcp_f32_e32 v165, v165
	v_rcp_f32_e32 v166, v166
	v_rcp_f32_e32 v167, v167
	v_rcp_f32_e32 v168, v168
	v_rcp_f32_e32 v169, v169
	v_rcp_f32_e32 v170, v170
	v_rcp_f32_e32 v171, v171
	v_rcp_f32_e32 v172, v172
	v_rcp_f32_e32 v173, v173
	v_rcp_f32_e32 v174, v174
	v_rcp_f32_e32 v175, v175
	s_waitcnt vmcnt(0)
	v_pk_add_f32 v[180:181], v[176:177], 1.0 op_sel_hi:[1,0] neg_lo:[1,0] neg_hi:[1,0]
	v_pk_add_f32 v[182:183], v[178:179], 1.0 op_sel_hi:[1,0] neg_lo:[1,0] neg_hi:[1,0]
	v_pk_mul_f32 v[160:161], v[160:161], v[180:181]
	v_pk_mul_f32 v[162:163], v[162:163], v[182:183]
	v_pk_mul_f32 v[164:165], v[164:165], v[180:181]
	v_pk_mul_f32 v[166:167], v[166:167], v[182:183]
	v_pk_mul_f32 v[168:169], v[168:169], v[180:181]
	v_pk_mul_f32 v[170:171], v[170:171], v[182:183]
	v_pk_mul_f32 v[172:173], v[172:173], v[180:181]
	v_pk_mul_f32 v[174:175], v[174:175], v[182:183]
	v_cvt_pk_bf16_f32 v60, v160, v161
	v_cvt_pk_bf16_f32 v61, v162, v163
	v_cvt_pk_bf16_f32 v56, v164, v165
	v_cvt_pk_bf16_f32 v57, v166, v167
	v_cvt_pk_bf16_f32 v52, v168, v169
	v_cvt_pk_bf16_f32 v53, v170, v171
	v_cvt_pk_bf16_f32 v48, v172, v173
	v_cvt_pk_bf16_f32 v49, v174, v175
	s_branch .Lep4_done
.Lep4_k0:
	v_cvt_pk_bf16_f32 v60, v60, v61
	v_cvt_pk_bf16_f32 v61, v62, v63
	v_cvt_pk_bf16_f32 v56, v56, v57
	v_cvt_pk_bf16_f32 v57, v58, v59
	v_cvt_pk_bf16_f32 v52, v52, v53
	v_cvt_pk_bf16_f32 v53, v54, v55
	v_cvt_pk_bf16_f32 v48, v48, v49
	v_cvt_pk_bf16_f32 v49, v50, v51
.Lep4_done:
	s_add_i32 s55, s54, 144
	s_cmpk_lt_u32 s55, 0x1a0
	s_cbranch_scc1 .Lep5_k0
	s_cmpk_lt_u32 s55, 0x3a0
	s_cbranch_scc1 .Lep5_k1
	s_cmpk_lt_u32 s55, 0x7a0
	s_cbranch_scc1 .Lep5_k0
	s_cmpk_lt_u32 s55, 0xba0
	s_cbranch_scc1 .Lep5_k3
	s_cmpk_lt_u32 s55, 0xda0
	s_cbranch_scc1 .Lep5_k1
	s_cmpk_lt_u32 s55, 0x13a0
	s_cbranch_scc1 .Lep5_k0
	s_cmpk_lt_u32 s55, 0x15a0
	s_cbranch_scc1 .Lep5_k1
	s_cmpk_lt_u32 s55, 0x21a0
	s_cbranch_scc0 .Lep5_k0
	v_mul_f32_e32 v160, 0xbfb8aa3b, v44
	v_mul_f32_e32 v161, 0xbfb8aa3b, v45
	v_mul_f32_e32 v162, 0xbfb8aa3b, v46
	v_mul_f32_e32 v163, 0xbfb8aa3b, v47
	v_mul_f32_e32 v164, 0xbfb8aa3b, v40
	v_mul_f32_e32 v165, 0xbfb8aa3b, v41
	v_mul_f32_e32 v166, 0xbfb8aa3b, v42
	v_mul_f32_e32 v167, 0xbfb8aa3b, v43
	v_mul_f32_e32 v168, 0xbfb8aa3b, v36
	v_mul_f32_e32 v169, 0xbfb8aa3b, v37
	v_mul_f32_e32 v170, 0xbfb8aa3b, v38
	v_mul_f32_e32 v171, 0xbfb8aa3b, v39
	v_mul_f32_e32 v172, 0xbfb8aa3b, v32
	v_mul_f32_e32 v173, 0xbfb8aa3b, v33
	v_mul_f32_e32 v174, 0xbfb8aa3b, v34
	v_mul_f32_e32 v175, 0xbfb8aa3b, v35
	v_exp_f32_e32 v160, v160
	v_exp_f32_e32 v161, v161
	v_exp_f32_e32 v162, v162
	v_exp_f32_e32 v163, v163
	v_exp_f32_e32 v164, v164
	v_exp_f32_e32 v165, v165
	v_exp_f32_e32 v166, v166
	v_exp_f32_e32 v167, v167
	v_exp_f32_e32 v168, v168
	v_exp_f32_e32 v169, v169
	v_exp_f32_e32 v170, v170
	v_exp_f32_e32 v171, v171
	v_exp_f32_e32 v172, v172
	v_exp_f32_e32 v173, v173
	v_exp_f32_e32 v174, v174
	v_exp_f32_e32 v175, v175
	v_add_f32_e32 v160, 1.0, v160
	v_add_f32_e32 v161, 1.0, v161
	v_add_f32_e32 v162, 1.0, v162
	v_add_f32_e32 v163, 1.0, v163
	v_add_f32_e32 v164, 1.0, v164
	v_add_f32_e32 v165, 1.0, v165
	v_add_f32_e32 v166, 1.0, v166
	v_add_f32_e32 v167, 1.0, v167
	v_add_f32_e32 v168, 1.0, v168
	v_add_f32_e32 v169, 1.0, v169
	v_add_f32_e32 v170, 1.0, v170
	v_add_f32_e32 v171, 1.0, v171
	v_add_f32_e32 v172, 1.0, v172
	v_add_f32_e32 v173, 1.0, v173
	v_add_f32_e32 v174, 1.0, v174
	v_add_f32_e32 v175, 1.0, v175
	v_rcp_f32_e32 v160, v160
	v_rcp_f32_e32 v161, v161
	v_rcp_f32_e32 v162, v162
	v_rcp_f32_e32 v163, v163
	v_rcp_f32_e32 v164, v164
	v_rcp_f32_e32 v165, v165
	v_rcp_f32_e32 v166, v166
	v_rcp_f32_e32 v167, v167
	v_rcp_f32_e32 v168, v168
	v_rcp_f32_e32 v169, v169
	v_rcp_f32_e32 v170, v170
	v_rcp_f32_e32 v171, v171
	v_rcp_f32_e32 v172, v172
	v_rcp_f32_e32 v173, v173
	v_rcp_f32_e32 v174, v174
	v_rcp_f32_e32 v175, v175
	v_cvt_pk_bf16_f32 v62, v160, v161
	v_cvt_pk_bf16_f32 v63, v162, v163
	v_cvt_pk_bf16_f32 v58, v164, v165
	v_cvt_pk_bf16_f32 v59, v166, v167
	v_cvt_pk_bf16_f32 v54, v168, v169
	v_cvt_pk_bf16_f32 v55, v170, v171
	v_cvt_pk_bf16_f32 v50, v172, v173
	v_cvt_pk_bf16_f32 v51, v174, v175
	s_branch .Lep5_done
; DEV float sigm(float x) { return rcpf(1.f + ex2(x * -1.4426950408889634f)); }
; DEV float siluf(float x) { return x * sigm(x); }
; DEV void inproj_item(const Params& p, int l, int tt, int tf, int ntt, int ntf, char* smem, int tid) {
;     ...
;   const int wid = tid >> 6, lane = tid & 63, fr = lane & 15, fq = lane >> 4, wr = wid >> 2, wc = wid & 3;
; #pragma unroll
;   for (int ai = 0; ai < 2; ++ai)
; #pragma unroll
;     for (int m = 0; m < 4; ++m) {
;       const int fb = __builtin_amdgcn_readfirstlane(f0 + ai * 128 + wr * 64 + m * 16);
;       const int kind = colkind(fb);
;       if (kind == 5) continue;
;       const int f = fb + fq * 4;
;       float4 lbv = make_float4(0.f, 0.f, 0.f, 0.f);
;       if (kind == 3) lbv = *(const float4*)(p.lb + l * 1024 + (f - C_HF));
;       if (kind == 4) lbv = *(const float4*)(p.lb + l * 1024 + 512 + (f - C_HF - 512));
; #pragma unroll
;       for (int bj = 0; bj < 2; ++bj)
; #pragma unroll
;         for (int n = 0; n < 2; ++n) {
;           const int r = t0 + bj * 128 + wc * 32 + n * 16 + fr;
;           const f32x4 a = acc[ai][bj][m][n];
;           float o0, o1, o2, o3;
;           if (kind == 0) { o0 = a[0]; o1 = a[1]; o2 = a[2]; o3 = a[3]; }
;           else if (kind == 1) { o0 = siluf(a[0]); o1 = siluf(a[1]); o2 = siluf(a[2]); o3 = siluf(a[3]); }
;           else if (kind == 2) { o0 = sigm(a[0]); o1 = sigm(a[1]); o2 = sigm(a[2]); o3 = sigm(a[3]); }
;           else {
;             o0 = (1.f - lbv.x) * sigm(-a[0]); o1 = (1.f - lbv.y) * sigm(-a[1]);
;             o2 = (1.f - lbv.z) * sigm(-a[2]); o3 = (1.f - lbv.w) * sigm(-a[3]);
;           }
;           uint2 o;
;           o.x = pack2(o0, o1);
;           o.y = pack2(o2, o3);
;           *(uint2*)(p.z + (long)r * NINP + f) = o;
;         }
;     }
.Lep5_k1:
	v_mul_f32_e32 v160, 0xbfb8aa3b, v44
	v_mul_f32_e32 v161, 0xbfb8aa3b, v45
	v_mul_f32_e32 v162, 0xbfb8aa3b, v46
	v_mul_f32_e32 v163, 0xbfb8aa3b, v47
	v_mul_f32_e32 v164, 0xbfb8aa3b, v40
	v_mul_f32_e32 v165, 0xbfb8aa3b, v41
	v_mul_f32_e32 v166, 0xbfb8aa3b, v42
	v_mul_f32_e32 v167, 0xbfb8aa3b, v43
	v_mul_f32_e32 v168, 0xbfb8aa3b, v36
	v_mul_f32_e32 v169, 0xbfb8aa3b, v37
	v_mul_f32_e32 v170, 0xbfb8aa3b, v38
	v_mul_f32_e32 v171, 0xbfb8aa3b, v39
	v_mul_f32_e32 v172, 0xbfb8aa3b, v32
	v_mul_f32_e32 v173, 0xbfb8aa3b, v33
	v_mul_f32_e32 v174, 0xbfb8aa3b, v34
	v_mul_f32_e32 v175, 0xbfb8aa3b, v35
	v_exp_f32_e32 v160, v160
	v_exp_f32_e32 v161, v161
	v_exp_f32_e32 v162, v162
	v_exp_f32_e32 v163, v163
	v_exp_f32_e32 v164, v164
	v_exp_f32_e32 v165, v165
	v_exp_f32_e32 v166, v166
	v_exp_f32_e32 v167, v167
	v_exp_f32_e32 v168, v168
	v_exp_f32_e32 v169, v169
	v_exp_f32_e32 v170, v170
	v_exp_f32_e32 v171, v171
	v_exp_f32_e32 v172, v172
	v_exp_f32_e32 v173, v173
	v_exp_f32_e32 v174, v174
	v_exp_f32_e32 v175, v175
	v_add_f32_e32 v160, 1.0, v160
	v_add_f32_e32 v161, 1.0, v161
	v_add_f32_e32 v162, 1.0, v162
	v_add_f32_e32 v163, 1.0, v163
	v_add_f32_e32 v164, 1.0, v164
	v_add_f32_e32 v165, 1.0, v165
	v_add_f32_e32 v166, 1.0, v166
	v_add_f32_e32 v167, 1.0, v167
	v_add_f32_e32 v168, 1.0, v168
	v_add_f32_e32 v169, 1.0, v169
	v_add_f32_e32 v170, 1.0, v170
	v_add_f32_e32 v171, 1.0, v171
	v_add_f32_e32 v172, 1.0, v172
	v_add_f32_e32 v173, 1.0, v173
	v_add_f32_e32 v174, 1.0, v174
	v_add_f32_e32 v175, 1.0, v175
	v_rcp_f32_e32 v160, v160
	v_rcp_f32_e32 v161, v161
	v_rcp_f32_e32 v162, v162
	v_rcp_f32_e32 v163, v163
	v_rcp_f32_e32 v164, v164
	v_rcp_f32_e32 v165, v165
	v_rcp_f32_e32 v166, v166
	v_rcp_f32_e32 v167, v167
	v_rcp_f32_e32 v168, v168
	v_rcp_f32_e32 v169, v169
	v_rcp_f32_e32 v170, v170
	v_rcp_f32_e32 v171, v171
	v_rcp_f32_e32 v172, v172
	v_rcp_f32_e32 v173, v173
	v_rcp_f32_e32 v174, v174
	v_rcp_f32_e32 v175, v175
	v_pk_mul_f32 v[160:161], v[44:45], v[160:161]
	v_pk_mul_f32 v[162:163], v[46:47], v[162:163]
	v_pk_mul_f32 v[164:165], v[40:41], v[164:165]
	v_pk_mul_f32 v[166:167], v[42:43], v[166:167]
	v_pk_mul_f32 v[168:169], v[36:37], v[168:169]
	v_pk_mul_f32 v[170:171], v[38:39], v[170:171]
	v_pk_mul_f32 v[172:173], v[32:33], v[172:173]
	v_pk_mul_f32 v[174:175], v[34:35], v[174:175]
	v_cvt_pk_bf16_f32 v62, v160, v161
	v_cvt_pk_bf16_f32 v63, v162, v163
	v_cvt_pk_bf16_f32 v58, v164, v165
	v_cvt_pk_bf16_f32 v59, v166, v167
	v_cvt_pk_bf16_f32 v54, v168, v169
	v_cvt_pk_bf16_f32 v55, v170, v171
	v_cvt_pk_bf16_f32 v50, v172, v173
	v_cvt_pk_bf16_f32 v51, v174, v175
	s_branch .Lep5_done
.Lep5_k3:
	s_add_i32 s7, s55, 0xfffff860
	s_lshl_b32 s7, s7, 2
	s_add_u32 s52, s40, s7
	s_addc_u32 s53, s41, 0
	global_load_dwordx4 v[176:179], v185, s[52:53]
	v_mul_f32_e32 v160, 0x3fb8aa3b, v44
	v_mul_f32_e32 v161, 0x3fb8aa3b, v45
	v_mul_f32_e32 v162, 0x3fb8aa3b, v46
	v_mul_f32_e32 v163, 0x3fb8aa3b, v47
	v_mul_f32_e32 v164, 0x3fb8aa3b, v40
	v_mul_f32_e32 v165, 0x3fb8aa3b, v41
	v_mul_f32_e32 v166, 0x3fb8aa3b, v42
	v_mul_f32_e32 v167, 0x3fb8aa3b, v43
	v_mul_f32_e32 v168, 0x3fb8aa3b, v36
	v_mul_f32_e32 v169, 0x3fb8aa3b, v37
	v_mul_f32_e32 v170, 0x3fb8aa3b, v38
	v_mul_f32_e32 v171, 0x3fb8aa3b, v39
	v_mul_f32_e32 v172, 0x3fb8aa3b, v32
	v_mul_f32_e32 v173, 0x3fb8aa3b, v33
	v_mul_f32_e32 v174, 0x3fb8aa3b, v34
	v_mul_f32_e32 v175, 0x3fb8aa3b, v35
	v_exp_f32_e32 v160, v160
	v_exp_f32_e32 v161, v161
	v_exp_f32_e32 v162, v162
	v_exp_f32_e32 v163, v163
	v_exp_f32_e32 v164, v164
	v_exp_f32_e32 v165, v165
	v_exp_f32_e32 v166, v166
	v_exp_f32_e32 v167, v167
	v_exp_f32_e32 v168, v168
	v_exp_f32_e32 v169, v169
	v_exp_f32_e32 v170, v170
	v_exp_f32_e32 v171, v171
	v_exp_f32_e32 v172, v172
	v_exp_f32_e32 v173, v173
	v_exp_f32_e32 v174, v174
	v_exp_f32_e32 v175, v175
	v_add_f32_e32 v160, 1.0, v160
	v_add_f32_e32 v161, 1.0, v161
	v_add_f32_e32 v162, 1.0, v162
	v_add_f32_e32 v163, 1.0, v163
	v_add_f32_e32 v164, 1.0, v164
	v_add_f32_e32 v165, 1.0, v165
	v_add_f32_e32 v166, 1.0, v166
	v_add_f32_e32 v167, 1.0, v167
	v_add_f32_e32 v168, 1.0, v168
	v_add_f32_e32 v169, 1.0, v169
	v_add_f32_e32 v170, 1.0, v170
	v_add_f32_e32 v171, 1.0, v171
	v_add_f32_e32 v172, 1.0, v172
	v_add_f32_e32 v173, 1.0, v173
	v_add_f32_e32 v174, 1.0, v174
	v_add_f32_e32 v175, 1.0, v175
	v_rcp_f32_e32 v160, v160
	v_rcp_f32_e32 v161, v161
	v_rcp_f32_e32 v162, v162
	v_rcp_f32_e32 v163, v163
	v_rcp_f32_e32 v164, v164
	v_rcp_f32_e32 v165, v165
	v_rcp_f32_e32 v166, v166
	v_rcp_f32_e32 v167, v167
	v_rcp_f32_e32 v168, v168
	v_rcp_f32_e32 v169, v169
	v_rcp_f32_e32 v170, v170
	v_rcp_f32_e32 v171, v171
	v_rcp_f32_e32 v172, v172
	v_rcp_f32_e32 v173, v173
	v_rcp_f32_e32 v174, v174
	v_rcp_f32_e32 v175, v175
	s_waitcnt vmcnt(0)
	v_pk_add_f32 v[180:181], v[176:177], 1.0 op_sel_hi:[1,0] neg_lo:[1,0] neg_hi:[1,0]
	v_pk_add_f32 v[182:183], v[178:179], 1.0 op_sel_hi:[1,0] neg_lo:[1,0] neg_hi:[1,0]
	v_pk_mul_f32 v[160:161], v[160:161], v[180:181]
	v_pk_mul_f32 v[162:163], v[162:163], v[182:183]
	v_pk_mul_f32 v[164:165], v[164:165], v[180:181]
	v_pk_mul_f32 v[166:167], v[166:167], v[182:183]
	v_pk_mul_f32 v[168:169], v[168:169], v[180:181]
	v_pk_mul_f32 v[170:171], v[170:171], v[182:183]
	v_pk_mul_f32 v[172:173], v[172:173], v[180:181]
	v_pk_mul_f32 v[174:175], v[174:175], v[182:183]
	v_cvt_pk_bf16_f32 v62, v160, v161
	v_cvt_pk_bf16_f32 v63, v162, v163
	v_cvt_pk_bf16_f32 v58, v164, v165
	v_cvt_pk_bf16_f32 v59, v166, v167
	v_cvt_pk_bf16_f32 v54, v168, v169
	v_cvt_pk_bf16_f32 v55, v170, v171
	v_cvt_pk_bf16_f32 v50, v172, v173
	v_cvt_pk_bf16_f32 v51, v174, v175
	s_branch .Lep5_done
; DEV float sigm(float x) { return rcpf(1.f + ex2(x * -1.4426950408889634f)); }
; DEV float siluf(float x) { return x * sigm(x); }
; DEV void inproj_item(const Params& p, int l, int tt, int tf, int ntt, int ntf, char* smem, int tid) {
;     ...
;   const int wid = tid >> 6, lane = tid & 63, fr = lane & 15, fq = lane >> 4, wr = wid >> 2, wc = wid & 3;
; #pragma unroll
;   for (int ai = 0; ai < 2; ++ai)
; #pragma unroll
;     for (int m = 0; m < 4; ++m) {
;       const int fb = __builtin_amdgcn_readfirstlane(f0 + ai * 128 + wr * 64 + m * 16);
;       const int kind = colkind(fb);
;       if (kind == 5) continue;
;       const int f = fb + fq * 4;
;       float4 lbv = make_float4(0.f, 0.f, 0.f, 0.f);
;       if (kind == 3) lbv = *(const float4*)(p.lb + l * 1024 + (f - C_HF));
;       if (kind == 4) lbv = *(const float4*)(p.lb + l * 1024 + 512 + (f - C_HF - 512));
; #pragma unroll
;       for (int bj = 0; bj < 2; ++bj)
; #pragma unroll
;         for (int n = 0; n < 2; ++n) {
;           const int r = t0 + bj * 128 + wc * 32 + n * 16 + fr;
;           const f32x4 a = acc[ai][bj][m][n];
;           float o0, o1, o2, o3;
;           if (kind == 0) { o0 = a[0]; o1 = a[1]; o2 = a[2]; o3 = a[3]; }
;           else if (kind == 1) { o0 = siluf(a[0]); o1 = siluf(a[1]); o2 = siluf(a[2]); o3 = siluf(a[3]); }
;           else if (kind == 2) { o0 = sigm(a[0]); o1 = sigm(a[1]); o2 = sigm(a[2]); o3 = sigm(a[3]); }
;           else {
;             o0 = (1.f - lbv.x) * sigm(-a[0]); o1 = (1.f - lbv.y) * sigm(-a[1]);
;             o2 = (1.f - lbv.z) * sigm(-a[2]); o3 = (1.f - lbv.w) * sigm(-a[3]);
;           }
;           uint2 o;
;           o.x = pack2(o0, o1);
;           o.y = pack2(o2, o3);
;           *(uint2*)(p.z + (long)r * NINP + f) = o;
;         }
;     }
.Lep5_k0:
	v_cvt_pk_bf16_f32 v62, v44, v45
	v_cvt_pk_bf16_f32 v63, v46, v47
	v_cvt_pk_bf16_f32 v58, v40, v41
	v_cvt_pk_bf16_f32 v59, v42, v43
	v_cvt_pk_bf16_f32 v54, v36, v37
	v_cvt_pk_bf16_f32 v55, v38, v39
	v_cvt_pk_bf16_f32 v50, v32, v33
	v_cvt_pk_bf16_f32 v51, v34, v35
.Lep5_done:
	s_nop 1
	v_permlane32_swap_b32_e32 v60, v62
	v_permlane32_swap_b32_e32 v61, v63
	v_permlane32_swap_b32_e32 v56, v58
	v_permlane32_swap_b32_e32 v57, v59
	v_permlane32_swap_b32_e32 v52, v54
	v_permlane32_swap_b32_e32 v53, v55
	v_permlane32_swap_b32_e32 v48, v50
	v_permlane32_swap_b32_e32 v49, v51
	v_permlane16_swap_b32_e32 v60, v62
	v_permlane16_swap_b32_e32 v61, v63
	v_permlane16_swap_b32_e32 v56, v58
	v_permlane16_swap_b32_e32 v57, v59
	v_permlane16_swap_b32_e32 v52, v54
	v_permlane16_swap_b32_e32 v53, v55
	v_permlane16_swap_b32_e32 v48, v50
	v_permlane16_swap_b32_e32 v49, v51
	global_store_dwordx4 v184, v[60:63], s[44:45] offset:256
	global_store_dwordx4 v184, v[56:59], s[46:47] offset:256
	global_store_dwordx4 v184, v[52:55], s[48:49] offset:256
	global_store_dwordx4 v184, v[48:51], s[50:51] offset:256
	s_add_i32 s55, s54, 160
	s_cmpk_lt_u32 s55, 0x1a0
	s_cbranch_scc1 .Lep6_k0
	s_cmpk_lt_u32 s55, 0x3a0
	s_cbranch_scc1 .Lep6_k1
	s_cmpk_lt_u32 s55, 0x7a0
	s_cbranch_scc1 .Lep6_k0
	s_cmpk_lt_u32 s55, 0xba0
	s_cbranch_scc1 .Lep6_k3
	s_cmpk_lt_u32 s55, 0xda0
	s_cbranch_scc1 .Lep6_k1
	s_cmpk_lt_u32 s55, 0x13a0
	s_cbranch_scc1 .Lep6_k0
	s_cmpk_lt_u32 s55, 0x15a0
	s_cbranch_scc1 .Lep6_k1
	s_cmpk_lt_u32 s55, 0x21a0
	s_cbranch_scc0 .Lep6_k0
	v_mul_f32_e32 v160, 0xbfb8aa3b, v28
	v_mul_f32_e32 v161, 0xbfb8aa3b, v29
	v_mul_f32_e32 v162, 0xbfb8aa3b, v30
	v_mul_f32_e32 v163, 0xbfb8aa3b, v31
	v_mul_f32_e32 v164, 0xbfb8aa3b, v24
	v_mul_f32_e32 v165, 0xbfb8aa3b, v25
	v_mul_f32_e32 v166, 0xbfb8aa3b, v26
	v_mul_f32_e32 v167, 0xbfb8aa3b, v27
	v_mul_f32_e32 v168, 0xbfb8aa3b, v20
	v_mul_f32_e32 v169, 0xbfb8aa3b, v21
	v_mul_f32_e32 v170, 0xbfb8aa3b, v22
	v_mul_f32_e32 v171, 0xbfb8aa3b, v23
	v_mul_f32_e32 v172, 0xbfb8aa3b, v16
	v_mul_f32_e32 v173, 0xbfb8aa3b, v17
	v_mul_f32_e32 v174, 0xbfb8aa3b, v18
	v_mul_f32_e32 v175, 0xbfb8aa3b, v19
	v_exp_f32_e32 v160, v160
	v_exp_f32_e32 v161, v161
	v_exp_f32_e32 v162, v162
	v_exp_f32_e32 v163, v163
	v_exp_f32_e32 v164, v164
	v_exp_f32_e32 v165, v165
	v_exp_f32_e32 v166, v166
	v_exp_f32_e32 v167, v167
	v_exp_f32_e32 v168, v168
	v_exp_f32_e32 v169, v169
	v_exp_f32_e32 v170, v170
	v_exp_f32_e32 v171, v171
	v_exp_f32_e32 v172, v172
	v_exp_f32_e32 v173, v173
	v_exp_f32_e32 v174, v174
	v_exp_f32_e32 v175, v175
	v_add_f32_e32 v160, 1.0, v160
	v_add_f32_e32 v161, 1.0, v161
	v_add_f32_e32 v162, 1.0, v162
	v_add_f32_e32 v163, 1.0, v163
	v_add_f32_e32 v164, 1.0, v164
	v_add_f32_e32 v165, 1.0, v165
	v_add_f32_e32 v166, 1.0, v166
	v_add_f32_e32 v167, 1.0, v167
	v_add_f32_e32 v168, 1.0, v168
	v_add_f32_e32 v169, 1.0, v169
	v_add_f32_e32 v170, 1.0, v170
	v_add_f32_e32 v171, 1.0, v171
	v_add_f32_e32 v172, 1.0, v172
	v_add_f32_e32 v173, 1.0, v173
	v_add_f32_e32 v174, 1.0, v174
	v_add_f32_e32 v175, 1.0, v175
	v_rcp_f32_e32 v160, v160
	v_rcp_f32_e32 v161, v161
	v_rcp_f32_e32 v162, v162
	v_rcp_f32_e32 v163, v163
	v_rcp_f32_e32 v164, v164
	v_rcp_f32_e32 v165, v165
	v_rcp_f32_e32 v166, v166
	v_rcp_f32_e32 v167, v167
	v_rcp_f32_e32 v168, v168
	v_rcp_f32_e32 v169, v169
	v_rcp_f32_e32 v170, v170
	v_rcp_f32_e32 v171, v171
	v_rcp_f32_e32 v172, v172
	v_rcp_f32_e32 v173, v173
	v_rcp_f32_e32 v174, v174
	v_rcp_f32_e32 v175, v175
	v_cvt_pk_bf16_f32 v28, v160, v161
	v_cvt_pk_bf16_f32 v29, v162, v163
	v_cvt_pk_bf16_f32 v24, v164, v165
	v_cvt_pk_bf16_f32 v25, v166, v167
	v_cvt_pk_bf16_f32 v20, v168, v169
	v_cvt_pk_bf16_f32 v21, v170, v171
	v_cvt_pk_bf16_f32 v16, v172, v173
	v_cvt_pk_bf16_f32 v17, v174, v175
	s_branch .Lep6_done
.Lep6_k1:
	v_mul_f32_e32 v160, 0xbfb8aa3b, v28
	v_mul_f32_e32 v161, 0xbfb8aa3b, v29
	v_mul_f32_e32 v162, 0xbfb8aa3b, v30
	v_mul_f32_e32 v163, 0xbfb8aa3b, v31
	v_mul_f32_e32 v164, 0xbfb8aa3b, v24
	v_mul_f32_e32 v165, 0xbfb8aa3b, v25
	v_mul_f32_e32 v166, 0xbfb8aa3b, v26
	v_mul_f32_e32 v167, 0xbfb8aa3b, v27
	v_mul_f32_e32 v168, 0xbfb8aa3b, v20
	v_mul_f32_e32 v169, 0xbfb8aa3b, v21
	v_mul_f32_e32 v170, 0xbfb8aa3b, v22
	v_mul_f32_e32 v171, 0xbfb8aa3b, v23
	v_mul_f32_e32 v172, 0xbfb8aa3b, v16
	v_mul_f32_e32 v173, 0xbfb8aa3b, v17
	v_mul_f32_e32 v174, 0xbfb8aa3b, v18
	v_mul_f32_e32 v175, 0xbfb8aa3b, v19
	v_exp_f32_e32 v160, v160
	v_exp_f32_e32 v161, v161
	v_exp_f32_e32 v162, v162
	v_exp_f32_e32 v163, v163
	v_exp_f32_e32 v164, v164
	v_exp_f32_e32 v165, v165
	v_exp_f32_e32 v166, v166
	v_exp_f32_e32 v167, v167
	v_exp_f32_e32 v168, v168
	v_exp_f32_e32 v169, v169
	v_exp_f32_e32 v170, v170
	v_exp_f32_e32 v171, v171
	v_exp_f32_e32 v172, v172
	v_exp_f32_e32 v173, v173
	v_exp_f32_e32 v174, v174
	v_exp_f32_e32 v175, v175
	v_add_f32_e32 v160, 1.0, v160
	v_add_f32_e32 v161, 1.0, v161
	v_add_f32_e32 v162, 1.0, v162
	v_add_f32_e32 v163, 1.0, v163
	v_add_f32_e32 v164, 1.0, v164
	v_add_f32_e32 v165, 1.0, v165
	v_add_f32_e32 v166, 1.0, v166
	v_add_f32_e32 v167, 1.0, v167
	v_add_f32_e32 v168, 1.0, v168
	v_add_f32_e32 v169, 1.0, v169
	v_add_f32_e32 v170, 1.0, v170
	v_add_f32_e32 v171, 1.0, v171
	v_add_f32_e32 v172, 1.0, v172
	v_add_f32_e32 v173, 1.0, v173
	v_add_f32_e32 v174, 1.0, v174
	v_add_f32_e32 v175, 1.0, v175
	v_rcp_f32_e32 v160, v160
	v_rcp_f32_e32 v161, v161
	v_rcp_f32_e32 v162, v162
	v_rcp_f32_e32 v163, v163
	v_rcp_f32_e32 v164, v164
	v_rcp_f32_e32 v165, v165
	v_rcp_f32_e32 v166, v166
	v_rcp_f32_e32 v167, v167
	v_rcp_f32_e32 v168, v168
	v_rcp_f32_e32 v169, v169
	v_rcp_f32_e32 v170, v170
	v_rcp_f32_e32 v171, v171
	v_rcp_f32_e32 v172, v172
	v_rcp_f32_e32 v173, v173
	v_rcp_f32_e32 v174, v174
	v_rcp_f32_e32 v175, v175
	v_pk_mul_f32 v[160:161], v[28:29], v[160:161]
	v_pk_mul_f32 v[162:163], v[30:31], v[162:163]
	v_pk_mul_f32 v[164:165], v[24:25], v[164:165]
	v_pk_mul_f32 v[166:167], v[26:27], v[166:167]
	v_pk_mul_f32 v[168:169], v[20:21], v[168:169]
	v_pk_mul_f32 v[170:171], v[22:23], v[170:171]
	v_pk_mul_f32 v[172:173], v[16:17], v[172:173]
	v_pk_mul_f32 v[174:175], v[18:19], v[174:175]
	v_cvt_pk_bf16_f32 v28, v160, v161
	v_cvt_pk_bf16_f32 v29, v162, v163
	v_cvt_pk_bf16_f32 v24, v164, v165
	v_cvt_pk_bf16_f32 v25, v166, v167
	v_cvt_pk_bf16_f32 v20, v168, v169
	v_cvt_pk_bf16_f32 v21, v170, v171
	v_cvt_pk_bf16_f32 v16, v172, v173
	v_cvt_pk_bf16_f32 v17, v174, v175
	s_branch .Lep6_done
; DEV float sigm(float x) { return rcpf(1.f + ex2(x * -1.4426950408889634f)); }
; DEV float siluf(float x) { return x * sigm(x); }
; DEV void inproj_item(const Params& p, int l, int tt, int tf, int ntt, int ntf, char* smem, int tid) {
;     ...
;   const int wid = tid >> 6, lane = tid & 63, fr = lane & 15, fq = lane >> 4, wr = wid >> 2, wc = wid & 3;
; #pragma unroll
;   for (int ai = 0; ai < 2; ++ai)
; #pragma unroll
;     for (int m = 0; m < 4; ++m) {
;       const int fb = __builtin_amdgcn_readfirstlane(f0 + ai * 128 + wr * 64 + m * 16);
;       const int kind = colkind(fb);
;       if (kind == 5) continue;
;       const int f = fb + fq * 4;
;       float4 lbv = make_float4(0.f, 0.f, 0.f, 0.f);
;       if (kind == 3) lbv = *(const float4*)(p.lb + l * 1024 + (f - C_HF));
;       if (kind == 4) lbv = *(const float4*)(p.lb + l * 1024 + 512 + (f - C_HF - 512));
; #pragma unroll
;       for (int bj = 0; bj < 2; ++bj)
; #pragma unroll
;         for (int n = 0; n < 2; ++n) {
;           const int r = t0 + bj * 128 + wc * 32 + n * 16 + fr;
;           const f32x4 a = acc[ai][bj][m][n];
;           float o0, o1, o2, o3;
;           if (kind == 0) { o0 = a[0]; o1 = a[1]; o2 = a[2]; o3 = a[3]; }
;           else if (kind == 1) { o0 = siluf(a[0]); o1 = siluf(a[1]); o2 = siluf(a[2]); o3 = siluf(a[3]); }
;           else if (kind == 2) { o0 = sigm(a[0]); o1 = sigm(a[1]); o2 = sigm(a[2]); o3 = sigm(a[3]); }
;           else {
;             o0 = (1.f - lbv.x) * sigm(-a[0]); o1 = (1.f - lbv.y) * sigm(-a[1]);
;             o2 = (1.f - lbv.z) * sigm(-a[2]); o3 = (1.f - lbv.w) * sigm(-a[3]);
;           }
;           uint2 o;
;           o.x = pack2(o0, o1);
;           o.y = pack2(o2, o3);
;           *(uint2*)(p.z + (long)r * NINP + f) = o;
;         }
;     }
.Lep6_k3:
	s_add_i32 s7, s55, 0xfffff860
	s_lshl_b32 s7, s7, 2
	s_add_u32 s52, s40, s7
	s_addc_u32 s53, s41, 0
	global_load_dwordx4 v[176:179], v185, s[52:53]
	v_mul_f32_e32 v160, 0x3fb8aa3b, v28
	v_mul_f32_e32 v161, 0x3fb8aa3b, v29
	v_mul_f32_e32 v162, 0x3fb8aa3b, v30
	v_mul_f32_e32 v163, 0x3fb8aa3b, v31
	v_mul_f32_e32 v164, 0x3fb8aa3b, v24
	v_mul_f32_e32 v165, 0x3fb8aa3b, v25
	v_mul_f32_e32 v166, 0x3fb8aa3b, v26
	v_mul_f32_e32 v167, 0x3fb8aa3b, v27
	v_mul_f32_e32 v168, 0x3fb8aa3b, v20
	v_mul_f32_e32 v169, 0x3fb8aa3b, v21
	v_mul_f32_e32 v170, 0x3fb8aa3b, v22
	v_mul_f32_e32 v171, 0x3fb8aa3b, v23
	v_mul_f32_e32 v172, 0x3fb8aa3b, v16
	v_mul_f32_e32 v173, 0x3fb8aa3b, v17
	v_mul_f32_e32 v174, 0x3fb8aa3b, v18
	v_mul_f32_e32 v175, 0x3fb8aa3b, v19
	v_exp_f32_e32 v160, v160
	v_exp_f32_e32 v161, v161
	v_exp_f32_e32 v162, v162
	v_exp_f32_e32 v163, v163
	v_exp_f32_e32 v164, v164
	v_exp_f32_e32 v165, v165
	v_exp_f32_e32 v166, v166
	v_exp_f32_e32 v167, v167
	v_exp_f32_e32 v168, v168
	v_exp_f32_e32 v169, v169
	v_exp_f32_e32 v170, v170
	v_exp_f32_e32 v171, v171
	v_exp_f32_e32 v172, v172
	v_exp_f32_e32 v173, v173
	v_exp_f32_e32 v174, v174
	v_exp_f32_e32 v175, v175
	v_add_f32_e32 v160, 1.0, v160
	v_add_f32_e32 v161, 1.0, v161
	v_add_f32_e32 v162, 1.0, v162
	v_add_f32_e32 v163, 1.0, v163
	v_add_f32_e32 v164, 1.0, v164
	v_add_f32_e32 v165, 1.0, v165
	v_add_f32_e32 v166, 1.0, v166
	v_add_f32_e32 v167, 1.0, v167
	v_add_f32_e32 v168, 1.0, v168
	v_add_f32_e32 v169, 1.0, v169
	v_add_f32_e32 v170, 1.0, v170
	v_add_f32_e32 v171, 1.0, v171
	v_add_f32_e32 v172, 1.0, v172
	v_add_f32_e32 v173, 1.0, v173
	v_add_f32_e32 v174, 1.0, v174
	v_add_f32_e32 v175, 1.0, v175
	v_rcp_f32_e32 v160, v160
	v_rcp_f32_e32 v161, v161
	v_rcp_f32_e32 v162, v162
	v_rcp_f32_e32 v163, v163
	v_rcp_f32_e32 v164, v164
	v_rcp_f32_e32 v165, v165
	v_rcp_f32_e32 v166, v166
	v_rcp_f32_e32 v167, v167
	v_rcp_f32_e32 v168, v168
	v_rcp_f32_e32 v169, v169
	v_rcp_f32_e32 v170, v170
	v_rcp_f32_e32 v171, v171
	v_rcp_f32_e32 v172, v172
	v_rcp_f32_e32 v173, v173
	v_rcp_f32_e32 v174, v174
	v_rcp_f32_e32 v175, v175
	s_waitcnt vmcnt(0)
	v_pk_add_f32 v[180:181], v[176:177], 1.0 op_sel_hi:[1,0] neg_lo:[1,0] neg_hi:[1,0]
	v_pk_add_f32 v[182:183], v[178:179], 1.0 op_sel_hi:[1,0] neg_lo:[1,0] neg_hi:[1,0]
	v_pk_mul_f32 v[160:161], v[160:161], v[180:181]
	v_pk_mul_f32 v[162:163], v[162:163], v[182:183]
	v_pk_mul_f32 v[164:165], v[164:165], v[180:181]
	v_pk_mul_f32 v[166:167], v[166:167], v[182:183]
	v_pk_mul_f32 v[168:169], v[168:169], v[180:181]
	v_pk_mul_f32 v[170:171], v[170:171], v[182:183]
	v_pk_mul_f32 v[172:173], v[172:173], v[180:181]
	v_pk_mul_f32 v[174:175], v[174:175], v[182:183]
	v_cvt_pk_bf16_f32 v28, v160, v161
	v_cvt_pk_bf16_f32 v29, v162, v163
	v_cvt_pk_bf16_f32 v24, v164, v165
	v_cvt_pk_bf16_f32 v25, v166, v167
	v_cvt_pk_bf16_f32 v20, v168, v169
	v_cvt_pk_bf16_f32 v21, v170, v171
	v_cvt_pk_bf16_f32 v16, v172, v173
	v_cvt_pk_bf16_f32 v17, v174, v175
	s_branch .Lep6_done
.Lep6_k0:
	v_cvt_pk_bf16_f32 v28, v28, v29
	v_cvt_pk_bf16_f32 v29, v30, v31
	v_cvt_pk_bf16_f32 v24, v24, v25
	v_cvt_pk_bf16_f32 v25, v26, v27
	v_cvt_pk_bf16_f32 v20, v20, v21
	v_cvt_pk_bf16_f32 v21, v22, v23
	v_cvt_pk_bf16_f32 v16, v16, v17
	v_cvt_pk_bf16_f32 v17, v18, v19
.Lep6_done:
	s_add_i32 s55, s54, 176
	s_cmpk_lt_u32 s55, 0x1a0
	s_cbranch_scc1 .Lep7_k0
	s_cmpk_lt_u32 s55, 0x3a0
	s_cbranch_scc1 .Lep7_k1
	s_cmpk_lt_u32 s55, 0x7a0
	s_cbranch_scc1 .Lep7_k0
	s_cmpk_lt_u32 s55, 0xba0
	s_cbranch_scc1 .Lep7_k3
	s_cmpk_lt_u32 s55, 0xda0
	s_cbranch_scc1 .Lep7_k1
	s_cmpk_lt_u32 s55, 0x13a0
	s_cbranch_scc1 .Lep7_k0
	s_cmpk_lt_u32 s55, 0x15a0
	s_cbranch_scc1 .Lep7_k1
	s_cmpk_lt_u32 s55, 0x21a0
	s_cbranch_scc0 .Lep7_k0
	v_mul_f32_e32 v160, 0xbfb8aa3b, v12
	v_mul_f32_e32 v161, 0xbfb8aa3b, v13
	v_mul_f32_e32 v162, 0xbfb8aa3b, v14
	v_mul_f32_e32 v163, 0xbfb8aa3b, v15
	v_mul_f32_e32 v164, 0xbfb8aa3b, v8
	v_mul_f32_e32 v165, 0xbfb8aa3b, v9
	v_mul_f32_e32 v166, 0xbfb8aa3b, v10
	v_mul_f32_e32 v167, 0xbfb8aa3b, v11
	v_mul_f32_e32 v168, 0xbfb8aa3b, v4
	v_mul_f32_e32 v169, 0xbfb8aa3b, v5
	v_mul_f32_e32 v170, 0xbfb8aa3b, v6
	v_mul_f32_e32 v171, 0xbfb8aa3b, v7
	v_mul_f32_e32 v172, 0xbfb8aa3b, v0
	v_mul_f32_e32 v173, 0xbfb8aa3b, v1
	v_mul_f32_e32 v174, 0xbfb8aa3b, v2
	v_mul_f32_e32 v175, 0xbfb8aa3b, v3
	v_exp_f32_e32 v160, v160
	v_exp_f32_e32 v161, v161
	v_exp_f32_e32 v162, v162
	v_exp_f32_e32 v163, v163
	v_exp_f32_e32 v164, v164
	v_exp_f32_e32 v165, v165
	v_exp_f32_e32 v166, v166
	v_exp_f32_e32 v167, v167
	v_exp_f32_e32 v168, v168
	v_exp_f32_e32 v169, v169
	v_exp_f32_e32 v170, v170
	v_exp_f32_e32 v171, v171
	v_exp_f32_e32 v172, v172
	v_exp_f32_e32 v173, v173
	v_exp_f32_e32 v174, v174
	v_exp_f32_e32 v175, v175
	v_add_f32_e32 v160, 1.0, v160
	v_add_f32_e32 v161, 1.0, v161
	v_add_f32_e32 v162, 1.0, v162
	v_add_f32_e32 v163, 1.0, v163
	v_add_f32_e32 v164, 1.0, v164
	v_add_f32_e32 v165, 1.0, v165
	v_add_f32_e32 v166, 1.0, v166
	v_add_f32_e32 v167, 1.0, v167
	v_add_f32_e32 v168, 1.0, v168
	v_add_f32_e32 v169, 1.0, v169
	v_add_f32_e32 v170, 1.0, v170
	v_add_f32_e32 v171, 1.0, v171
	v_add_f32_e32 v172, 1.0, v172
	v_add_f32_e32 v173, 1.0, v173
	v_add_f32_e32 v174, 1.0, v174
	v_add_f32_e32 v175, 1.0, v175
	v_rcp_f32_e32 v160, v160
	v_rcp_f32_e32 v161, v161
	v_rcp_f32_e32 v162, v162
	v_rcp_f32_e32 v163, v163
	v_rcp_f32_e32 v164, v164
	v_rcp_f32_e32 v165, v165
	v_rcp_f32_e32 v166, v166
	v_rcp_f32_e32 v167, v167
	v_rcp_f32_e32 v168, v168
	v_rcp_f32_e32 v169, v169
	v_rcp_f32_e32 v170, v170
	v_rcp_f32_e32 v171, v171
	v_rcp_f32_e32 v172, v172
	v_rcp_f32_e32 v173, v173
	v_rcp_f32_e32 v174, v174
	v_rcp_f32_e32 v175, v175
	v_cvt_pk_bf16_f32 v30, v160, v161
	v_cvt_pk_bf16_f32 v31, v162, v163
	v_cvt_pk_bf16_f32 v26, v164, v165
	v_cvt_pk_bf16_f32 v27, v166, v167
	v_cvt_pk_bf16_f32 v22, v168, v169
	v_cvt_pk_bf16_f32 v23, v170, v171
	v_cvt_pk_bf16_f32 v18, v172, v173
	v_cvt_pk_bf16_f32 v19, v174, v175
	s_branch .Lep7_done
; DEV float sigm(float x) { return rcpf(1.f + ex2(x * -1.4426950408889634f)); }
; DEV float siluf(float x) { return x * sigm(x); }
; DEV void inproj_item(const Params& p, int l, int tt, int tf, int ntt, int ntf, char* smem, int tid) {
;     ...
;   const int wid = tid >> 6, lane = tid & 63, fr = lane & 15, fq = lane >> 4, wr = wid >> 2, wc = wid & 3;
; #pragma unroll
;   for (int ai = 0; ai < 2; ++ai)
; #pragma unroll
;     for (int m = 0; m < 4; ++m) {
;       const int fb = __builtin_amdgcn_readfirstlane(f0 + ai * 128 + wr * 64 + m * 16);
;       const int kind = colkind(fb);
;       if (kind == 5) continue;
;       const int f = fb + fq * 4;
;       float4 lbv = make_float4(0.f, 0.f, 0.f, 0.f);
;       if (kind == 3) lbv = *(const float4*)(p.lb + l * 1024 + (f - C_HF));
;       if (kind == 4) lbv = *(const float4*)(p.lb + l * 1024 + 512 + (f - C_HF - 512));
; #pragma unroll
;       for (int bj = 0; bj < 2; ++bj)
; #pragma unroll
;         for (int n = 0; n < 2; ++n) {
;           const int r = t0 + bj * 128 + wc * 32 + n * 16 + fr;
;           const f32x4 a = acc[ai][bj][m][n];
;           float o0, o1, o2, o3;
;           if (kind == 0) { o0 = a[0]; o1 = a[1]; o2 = a[2]; o3 = a[3]; }
;           else if (kind == 1) { o0 = siluf(a[0]); o1 = siluf(a[1]); o2 = siluf(a[2]); o3 = siluf(a[3]); }
;           else if (kind == 2) { o0 = sigm(a[0]); o1 = sigm(a[1]); o2 = sigm(a[2]); o3 = sigm(a[3]); }
;           else {
;             o0 = (1.f - lbv.x) * sigm(-a[0]); o1 = (1.f - lbv.y) * sigm(-a[1]);
;             o2 = (1.f - lbv.z) * sigm(-a[2]); o3 = (1.f - lbv.w) * sigm(-a[3]);
;           }
;           uint2 o;
;           o.x = pack2(o0, o1);
;           o.y = pack2(o2, o3);
;           *(uint2*)(p.z + (long)r * NINP + f) = o;
;         }
;     }
.Lep7_k1:
	v_mul_f32_e32 v160, 0xbfb8aa3b, v12
	v_mul_f32_e32 v161, 0xbfb8aa3b, v13
	v_mul_f32_e32 v162, 0xbfb8aa3b, v14
	v_mul_f32_e32 v163, 0xbfb8aa3b, v15
	v_mul_f32_e32 v164, 0xbfb8aa3b, v8
	v_mul_f32_e32 v165, 0xbfb8aa3b, v9
	v_mul_f32_e32 v166, 0xbfb8aa3b, v10
	v_mul_f32_e32 v167, 0xbfb8aa3b, v11
	v_mul_f32_e32 v168, 0xbfb8aa3b, v4
	v_mul_f32_e32 v169, 0xbfb8aa3b, v5
	v_mul_f32_e32 v170, 0xbfb8aa3b, v6
	v_mul_f32_e32 v171, 0xbfb8aa3b, v7
	v_mul_f32_e32 v172, 0xbfb8aa3b, v0
	v_mul_f32_e32 v173, 0xbfb8aa3b, v1
	v_mul_f32_e32 v174, 0xbfb8aa3b, v2
	v_mul_f32_e32 v175, 0xbfb8aa3b, v3
	v_exp_f32_e32 v160, v160
	v_exp_f32_e32 v161, v161
	v_exp_f32_e32 v162, v162
	v_exp_f32_e32 v163, v163
	v_exp_f32_e32 v164, v164
	v_exp_f32_e32 v165, v165
	v_exp_f32_e32 v166, v166
	v_exp_f32_e32 v167, v167
	v_exp_f32_e32 v168, v168
	v_exp_f32_e32 v169, v169
	v_exp_f32_e32 v170, v170
	v_exp_f32_e32 v171, v171
	v_exp_f32_e32 v172, v172
	v_exp_f32_e32 v173, v173
	v_exp_f32_e32 v174, v174
	v_exp_f32_e32 v175, v175
	v_add_f32_e32 v160, 1.0, v160
	v_add_f32_e32 v161, 1.0, v161
	v_add_f32_e32 v162, 1.0, v162
	v_add_f32_e32 v163, 1.0, v163
	v_add_f32_e32 v164, 1.0, v164
	v_add_f32_e32 v165, 1.0, v165
	v_add_f32_e32 v166, 1.0, v166
	v_add_f32_e32 v167, 1.0, v167
	v_add_f32_e32 v168, 1.0, v168
	v_add_f32_e32 v169, 1.0, v169
	v_add_f32_e32 v170, 1.0, v170
	v_add_f32_e32 v171, 1.0, v171
	v_add_f32_e32 v172, 1.0, v172
	v_add_f32_e32 v173, 1.0, v173
	v_add_f32_e32 v174, 1.0, v174
	v_add_f32_e32 v175, 1.0, v175
	v_rcp_f32_e32 v160, v160
	v_rcp_f32_e32 v161, v161
	v_rcp_f32_e32 v162, v162
	v_rcp_f32_e32 v163, v163
	v_rcp_f32_e32 v164, v164
	v_rcp_f32_e32 v165, v165
	v_rcp_f32_e32 v166, v166
	v_rcp_f32_e32 v167, v167
	v_rcp_f32_e32 v168, v168
	v_rcp_f32_e32 v169, v169
	v_rcp_f32_e32 v170, v170
	v_rcp_f32_e32 v171, v171
	v_rcp_f32_e32 v172, v172
	v_rcp_f32_e32 v173, v173
	v_rcp_f32_e32 v174, v174
	v_rcp_f32_e32 v175, v175
	v_pk_mul_f32 v[160:161], v[12:13], v[160:161]
	v_pk_mul_f32 v[162:163], v[14:15], v[162:163]
	v_pk_mul_f32 v[164:165], v[8:9], v[164:165]
	v_pk_mul_f32 v[166:167], v[10:11], v[166:167]
	v_pk_mul_f32 v[168:169], v[4:5], v[168:169]
	v_pk_mul_f32 v[170:171], v[6:7], v[170:171]
	v_pk_mul_f32 v[172:173], v[0:1], v[172:173]
	v_pk_mul_f32 v[174:175], v[2:3], v[174:175]
	v_cvt_pk_bf16_f32 v30, v160, v161
	v_cvt_pk_bf16_f32 v31, v162, v163
	v_cvt_pk_bf16_f32 v26, v164, v165
	v_cvt_pk_bf16_f32 v27, v166, v167
	v_cvt_pk_bf16_f32 v22, v168, v169
	v_cvt_pk_bf16_f32 v23, v170, v171
	v_cvt_pk_bf16_f32 v18, v172, v173
	v_cvt_pk_bf16_f32 v19, v174, v175
	s_branch .Lep7_done
.Lep7_k3:
	s_add_i32 s7, s55, 0xfffff860
	s_lshl_b32 s7, s7, 2
	s_add_u32 s52, s40, s7
	s_addc_u32 s53, s41, 0
	global_load_dwordx4 v[176:179], v185, s[52:53]
	v_mul_f32_e32 v160, 0x3fb8aa3b, v12
	v_mul_f32_e32 v161, 0x3fb8aa3b, v13
	v_mul_f32_e32 v162, 0x3fb8aa3b, v14
	v_mul_f32_e32 v163, 0x3fb8aa3b, v15
	v_mul_f32_e32 v164, 0x3fb8aa3b, v8
	v_mul_f32_e32 v165, 0x3fb8aa3b, v9
	v_mul_f32_e32 v166, 0x3fb8aa3b, v10
	v_mul_f32_e32 v167, 0x3fb8aa3b, v11
	v_mul_f32_e32 v168, 0x3fb8aa3b, v4
	v_mul_f32_e32 v169, 0x3fb8aa3b, v5
	v_mul_f32_e32 v170, 0x3fb8aa3b, v6
	v_mul_f32_e32 v171, 0x3fb8aa3b, v7
	v_mul_f32_e32 v172, 0x3fb8aa3b, v0
	v_mul_f32_e32 v173, 0x3fb8aa3b, v1
	v_mul_f32_e32 v174, 0x3fb8aa3b, v2
	v_mul_f32_e32 v175, 0x3fb8aa3b, v3
	v_exp_f32_e32 v160, v160
	v_exp_f32_e32 v161, v161
	v_exp_f32_e32 v162, v162
	v_exp_f32_e32 v163, v163
	v_exp_f32_e32 v164, v164
	v_exp_f32_e32 v165, v165
	v_exp_f32_e32 v166, v166
	v_exp_f32_e32 v167, v167
	v_exp_f32_e32 v168, v168
	v_exp_f32_e32 v169, v169
	v_exp_f32_e32 v170, v170
	v_exp_f32_e32 v171, v171
	v_exp_f32_e32 v172, v172
	v_exp_f32_e32 v173, v173
	v_exp_f32_e32 v174, v174
	v_exp_f32_e32 v175, v175
	v_add_f32_e32 v160, 1.0, v160
	v_add_f32_e32 v161, 1.0, v161
	v_add_f32_e32 v162, 1.0, v162
	v_add_f32_e32 v163, 1.0, v163
	v_add_f32_e32 v164, 1.0, v164
	v_add_f32_e32 v165, 1.0, v165
	v_add_f32_e32 v166, 1.0, v166
	v_add_f32_e32 v167, 1.0, v167
	v_add_f32_e32 v168, 1.0, v168
	v_add_f32_e32 v169, 1.0, v169
	v_add_f32_e32 v170, 1.0, v170
	v_add_f32_e32 v171, 1.0, v171
	v_add_f32_e32 v172, 1.0, v172
	v_add_f32_e32 v173, 1.0, v173
	v_add_f32_e32 v174, 1.0, v174
	v_add_f32_e32 v175, 1.0, v175
	v_rcp_f32_e32 v160, v160
	v_rcp_f32_e32 v161, v161
	v_rcp_f32_e32 v162, v162
	v_rcp_f32_e32 v163, v163
	v_rcp_f32_e32 v164, v164
	v_rcp_f32_e32 v165, v165
	v_rcp_f32_e32 v166, v166
	v_rcp_f32_e32 v167, v167
	v_rcp_f32_e32 v168, v168
	v_rcp_f32_e32 v169, v169
	v_rcp_f32_e32 v170, v170
	v_rcp_f32_e32 v171, v171
	v_rcp_f32_e32 v172, v172
	v_rcp_f32_e32 v173, v173
	v_rcp_f32_e32 v174, v174
	v_rcp_f32_e32 v175, v175
	s_waitcnt vmcnt(0)
	v_pk_add_f32 v[180:181], v[176:177], 1.0 op_sel_hi:[1,0] neg_lo:[1,0] neg_hi:[1,0]
	v_pk_add_f32 v[182:183], v[178:179], 1.0 op_sel_hi:[1,0] neg_lo:[1,0] neg_hi:[1,0]
	v_pk_mul_f32 v[160:161], v[160:161], v[180:181]
	v_pk_mul_f32 v[162:163], v[162:163], v[182:183]
	v_pk_mul_f32 v[164:165], v[164:165], v[180:181]
	v_pk_mul_f32 v[166:167], v[166:167], v[182:183]
	v_pk_mul_f32 v[168:169], v[168:169], v[180:181]
	v_pk_mul_f32 v[170:171], v[170:171], v[182:183]
	v_pk_mul_f32 v[172:173], v[172:173], v[180:181]
	v_pk_mul_f32 v[174:175], v[174:175], v[182:183]
	v_cvt_pk_bf16_f32 v30, v160, v161
	v_cvt_pk_bf16_f32 v31, v162, v163
	v_cvt_pk_bf16_f32 v26, v164, v165
	v_cvt_pk_bf16_f32 v27, v166, v167
	v_cvt_pk_bf16_f32 v22, v168, v169
	v_cvt_pk_bf16_f32 v23, v170, v171
	v_cvt_pk_bf16_f32 v18, v172, v173
	v_cvt_pk_bf16_f32 v19, v174, v175
	s_branch .Lep7_done
.Lep7_k0:
	v_cvt_pk_bf16_f32 v30, v12, v13
	v_cvt_pk_bf16_f32 v31, v14, v15
	v_cvt_pk_bf16_f32 v26, v8, v9
	v_cvt_pk_bf16_f32 v27, v10, v11
	v_cvt_pk_bf16_f32 v22, v4, v5
	v_cvt_pk_bf16_f32 v23, v6, v7
	v_cvt_pk_bf16_f32 v18, v0, v1
	v_cvt_pk_bf16_f32 v19, v2, v3
.Lep7_done:
	s_nop 1
	v_permlane32_swap_b32_e32 v28, v30
	v_permlane32_swap_b32_e32 v29, v31
	v_permlane32_swap_b32_e32 v24, v26
	v_permlane32_swap_b32_e32 v25, v27
	v_permlane32_swap_b32_e32 v20, v22
	v_permlane32_swap_b32_e32 v21, v23
	v_permlane32_swap_b32_e32 v16, v18
	v_permlane32_swap_b32_e32 v17, v19
	v_permlane16_swap_b32_e32 v28, v30
	v_permlane16_swap_b32_e32 v29, v31
	v_permlane16_swap_b32_e32 v24, v26
	v_permlane16_swap_b32_e32 v25, v27
	v_permlane16_swap_b32_e32 v20, v22
	v_permlane16_swap_b32_e32 v21, v23
	v_permlane16_swap_b32_e32 v16, v18
	v_permlane16_swap_b32_e32 v17, v19
	global_store_dwordx4 v184, v[28:31], s[44:45] offset:320
	global_store_dwordx4 v184, v[24:27], s[46:47] offset:320
	global_store_dwordx4 v184, v[20:23], s[48:49] offset:320
	global_store_dwordx4 v184, v[16:19], s[50:51] offset:320
	s_branch .LBB0_166
